# hand-written P0 (weights LDS-staged, x rows), final norm, SSM discretisation batched, prompt attn K/V loads hoisted, sample attention rewritten with all loads in flight
# speedup vs baseline: 1.0232x; 1.0232x over previous
; __device__ __forceinline__ void p0_prologue(const Args& a, LAS unsigned char* lds, int wave, int lane) {
;     ...
;             const float are = a.in[14][gt], aim = a.in[15][gt], dt = expf(a.in[16][g]);
;             const float mag = expf(are * dt), ang = aim * dt;
;             float sn, cs; sincosf(ang, &sn, &cs);
;             const float lre = mag * cs, lim = mag * sn, den = are * are + aim * aim, nre = lre - 1.0f;
;             const float cre = (nre * are + lim * aim) / den, cim = (lim * are - nre * aim) / den;
;             float pre = lre, pim = lim;
; #pragma unroll
;             for (int i = 0; i < 7; ++i) { const float t = pre * pre - pim * pim; pim = 2.f * pre * pim; pre = t; }
;             float* lam = (float*)(ws + WS_LAM) + gt * 4; lam[0] = lre; lam[1] = lim; lam[2] = pre; lam[3] = pim;
;             float* bb = (float*)(ws + WS_BB) + gt * 32; const float* bre = a.in[17] + gt * 16; const float* bim = a.in[18] + gt * 16;
; #pragma unroll
;             for (int c = 0; c < 16; ++c) { bb[c] = cre * bre[c] - cim * bim[c]; bb[16 + c] = cre * bim[c] + cim * bre[c]; }
.LBB0_111:
	s_or_b64 exec, exec, s[8:9]
	s_waitcnt vmcnt(0)
	v_mul_f32_e32 v2, v6, v2
	s_mov_b32 s3, 0x3fb8aa3b
	v_mul_f32_e32 v3, 0x3fb8aa3b, v2
	v_fma_f32 v4, v2, s3, -v3
	v_rndne_f32_e32 v5, v3
	v_mul_f32_e32 v11, v9, v9
	v_mov_b32_e32 v15, 0x3c0881c4
	v_fmamk_f32 v4, v2, 0x32a5705f, v4
	v_sub_f32_e32 v3, v3, v5
	v_fmac_f32_e32 v15, 0xb94c1982, v11
	v_add_f32_e32 v3, v3, v4
	v_fmaak_f32 v15, v11, v15, 0xbe2aaa9d
	v_exp_f32_e32 v3, v3
	v_cvt_i32_f32_e32 v4, v5
	v_mul_f32_e32 v15, v11, v15
	v_fmac_f32_e32 v9, v9, v15
	v_mov_b32_e32 v15, 0xbab64f3b
	v_fmac_f32_e32 v15, 0x37d75334, v11
	s_mov_b32 s3, 0xc2ce8ed0
	v_fmaak_f32 v15, v11, v15, 0x3d2aabf7
	v_ldexp_f32 v3, v3, v4
	v_cmp_ngt_f32_e32 vcc, s3, v2
	s_mov_b32 s3, 0x42b17218
	v_fmaak_f32 v15, v11, v15, 0xbf000004
	v_cndmask_b32_e32 v3, 0, v3, vcc
	v_mov_b32_e32 v4, 0x7f800000
	v_cmp_nlt_f32_e32 vcc, s3, v2
	v_fma_f32 v11, v11, v15, 1.0
	v_lshlrev_b32_e32 v15, 30, v10
	v_and_b32_e32 v10, 1, v10
	v_cndmask_b32_e32 v14, v4, v3, vcc
	v_cmp_eq_u32_e32 vcc, 0, v10
	s_brev_b32 s3, 1
	v_xor_b32_e32 v8, v8, v7
	v_cndmask_b32_e32 v10, v11, v9, vcc
	v_xor_b32_e32 v9, 0x80000000, v9
	v_cndmask_b32_e32 v9, v9, v11, vcc
	v_bitop3_b32 v9, v9, v15, s3 bitop3:0x78
	s_movk_i32 s3, 0x1f8
	v_and_b32_e32 v16, 0x80000000, v15
	v_xor_b32_e32 v8, v8, v10
	v_mov_b32_e32 v10, 0x7fc00000
	v_cmp_class_f32_e64 vcc, v7, s3
	v_xor_b32_e32 v8, v8, v16
	v_lshl_add_u64 v[12:13], v[128:129], 4, v[24:25]
	v_cndmask_b32_e32 v7, v10, v9, vcc
	v_cndmask_b32_e32 v9, v10, v8, vcc
	v_mul_f32_e32 v8, v14, v7
	v_mul_f32_e32 v9, v14, v9
	v_add_f32_e32 v11, v8, v8
	v_mul_f32_e32 v10, v9, v9
	v_mul_f32_e32 v11, v11, v9
	v_fma_f32 v10, v8, v8, -v10
	v_mul_f32_e32 v15, v11, v11
	v_fma_f32 v15, v10, v10, -v15
	v_add_f32_e32 v10, v10, v10
	v_mul_f32_e32 v10, v11, v10
	v_mul_f32_e32 v11, v10, v10
	v_fma_f32 v11, v15, v15, -v11
	v_add_f32_e32 v15, v15, v15
	v_mul_f32_e32 v10, v10, v15
	v_mul_f32_e32 v15, v10, v10
	v_fma_f32 v15, v11, v11, -v15
	v_add_f32_e32 v11, v11, v11
	v_mul_f32_e32 v10, v10, v11
	v_mul_f32_e32 v11, v10, v10
	v_fma_f32 v11, v15, v15, -v11
	v_add_f32_e32 v15, v15, v15
	v_mul_f32_e32 v10, v10, v15
	v_mul_f32_e32 v15, v10, v10
	v_fma_f32 v15, v11, v11, -v15
	v_add_f32_e32 v11, v11, v11
	v_mul_f32_e32 v11, v10, v11
	v_mul_f32_e32 v10, v11, v11
	s_mov_b32 s3, 0x154fc000
	v_fma_f32 v10, v15, v15, -v10
	v_add_f32_e32 v15, v15, v15
	v_add_co_u32_e32 v12, vcc, s3, v12
	v_lshlrev_b64 v[4:5], 6, v[128:129]
	v_mul_f32_e32 v11, v11, v15
	v_addc_co_u32_e32 v13, vcc, 0, v13, vcc
	v_lshl_add_u64 v[2:3], s[22:23], 0, v[4:5]
	v_lshl_add_u64 v[4:5], s[38:39], 0, v[4:5]
	global_store_dwordx4 v[12:13], v[8:11], off
	global_load_dwordx4 v[96:99], v[2:3], off
	global_load_dwordx4 v[100:103], v[2:3], off offset:16
	global_load_dwordx4 v[104:107], v[2:3], off offset:32
	global_load_dwordx4 v[108:111], v[2:3], off offset:48
	global_load_dwordx4 v[206:209], v[4:5], off
	global_load_dwordx4 v[210:213], v[4:5], off offset:16
	global_load_dwordx4 v[214:217], v[4:5], off offset:32
	global_load_dwordx4 v[218:221], v[4:5], off offset:48
	v_mul_f32_e32 v13, v1, v1
	v_fma_f32 v7, v14, v7, -1.0
	v_mul_f32_e32 v14, v1, v9
	v_fmac_f32_e32 v14, v6, v7
	v_fmac_f32_e32 v13, v6, v6
	v_div_scale_f32 v15, s[8:9], v13, v13, v14
	v_rcp_f32_e32 v16, v15
	v_mul_f32_e32 v1, v1, v7
	v_fma_f32 v1, v6, v9, -v1
	v_lshlrev_b64 v[10:11], 7, v[128:129]
	v_fma_f32 v6, -v15, v16, 1.0
	v_fmac_f32_e32 v16, v6, v16
	v_div_scale_f32 v6, vcc, v14, v13, v14
	v_mul_f32_e32 v7, v6, v16
	v_fma_f32 v9, -v15, v7, v6
	v_fmac_f32_e32 v7, v9, v16
	v_div_scale_f32 v9, s[8:9], v13, v13, v1
	v_fma_f32 v6, -v15, v7, v6
	v_rcp_f32_e32 v15, v9
	v_div_fmas_f32 v6, v6, v16, v7
	v_div_fixup_f32 v14, v6, v13, v14
	v_lshl_add_u64 v[10:11], v[24:25], 0, v[10:11]
	v_fma_f32 v6, -v9, v15, 1.0
	v_fmac_f32_e32 v15, v6, v15
	v_div_scale_f32 v6, vcc, v1, v13, v1
	v_mul_f32_e32 v7, v6, v15
	v_fma_f32 v16, -v9, v7, v6
	v_fmac_f32_e32 v7, v16, v15
	v_fma_f32 v6, -v9, v7, v6
	v_div_fmas_f32 v6, v6, v15, v7
	v_div_fixup_f32 v1, v6, v13, v1
	s_mov_b64 s[8:9], 0x1550c000
	v_lshl_add_u64 v[6:7], v[10:11], 0, s[8:9]
	s_waitcnt vmcnt(0)
	v_mul_f32_e32 v222, v1, v206
	v_mul_f32_e32 v223, v1, v96
	v_fma_f32 v96, v14, v96, -v222
	v_fma_f32 v206, v14, v206, v223
	v_mul_f32_e32 v222, v1, v207
	v_mul_f32_e32 v223, v1, v97
	v_fma_f32 v97, v14, v97, -v222
	v_fma_f32 v207, v14, v207, v223
	v_mul_f32_e32 v222, v1, v208
	v_mul_f32_e32 v223, v1, v98
	v_fma_f32 v98, v14, v98, -v222
	v_fma_f32 v208, v14, v208, v223
	v_mul_f32_e32 v222, v1, v209
	v_mul_f32_e32 v223, v1, v99
	v_fma_f32 v99, v14, v99, -v222
	v_fma_f32 v209, v14, v209, v223
	v_mul_f32_e32 v222, v1, v210
	v_mul_f32_e32 v223, v1, v100
	v_fma_f32 v100, v14, v100, -v222
	v_fma_f32 v210, v14, v210, v223
	v_mul_f32_e32 v222, v1, v211
	v_mul_f32_e32 v223, v1, v101
	v_fma_f32 v101, v14, v101, -v222
	v_fma_f32 v211, v14, v211, v223
	v_mul_f32_e32 v222, v1, v212
	v_mul_f32_e32 v223, v1, v102
	v_fma_f32 v102, v14, v102, -v222
	v_fma_f32 v212, v14, v212, v223
	v_mul_f32_e32 v222, v1, v213
	v_mul_f32_e32 v223, v1, v103
	v_fma_f32 v103, v14, v103, -v222
	v_fma_f32 v213, v14, v213, v223
	v_mul_f32_e32 v222, v1, v214
	v_mul_f32_e32 v223, v1, v104
	v_fma_f32 v104, v14, v104, -v222
	v_fma_f32 v214, v14, v214, v223
	v_mul_f32_e32 v222, v1, v215
	v_mul_f32_e32 v223, v1, v105
	v_fma_f32 v105, v14, v105, -v222
	v_fma_f32 v215, v14, v215, v223
	v_mul_f32_e32 v222, v1, v216
	v_mul_f32_e32 v223, v1, v106
	v_fma_f32 v106, v14, v106, -v222
	v_fma_f32 v216, v14, v216, v223
	v_mul_f32_e32 v222, v1, v217
	v_mul_f32_e32 v223, v1, v107
	v_fma_f32 v107, v14, v107, -v222
	v_fma_f32 v217, v14, v217, v223
	v_mul_f32_e32 v222, v1, v218
	v_mul_f32_e32 v223, v1, v108
	v_fma_f32 v108, v14, v108, -v222
	v_fma_f32 v218, v14, v218, v223
	v_mul_f32_e32 v222, v1, v219
	v_mul_f32_e32 v223, v1, v109
	v_fma_f32 v109, v14, v109, -v222
	v_fma_f32 v219, v14, v219, v223
	v_mul_f32_e32 v222, v1, v220
	v_mul_f32_e32 v223, v1, v110
	v_fma_f32 v110, v14, v110, -v222
	v_fma_f32 v220, v14, v220, v223
	v_mul_f32_e32 v222, v1, v221
	v_mul_f32_e32 v223, v1, v111
	v_fma_f32 v111, v14, v111, -v222
	v_fma_f32 v221, v14, v221, v223
	global_store_dwordx4 v[6:7], v[96:99], off
	global_store_dwordx4 v[6:7], v[100:103], off offset:16
	global_store_dwordx4 v[6:7], v[104:107], off offset:32
	global_store_dwordx4 v[6:7], v[108:111], off offset:48
	global_store_dwordx4 v[6:7], v[206:209], off offset:64
	global_store_dwordx4 v[6:7], v[210:213], off offset:80
	global_store_dwordx4 v[6:7], v[214:217], off offset:96
	global_store_dwordx4 v[6:7], v[218:221], off offset:112

; #define LAS __attribute__((address_space(3)))
; __device__ __forceinline__ void attn_prompt_item(LAS unsigned char* lds, const bf16_t* qkvb, bf16_t* og, float* lse, int it, int tid, int wave, int lane) {
;     const int b = it / 768, rem0 = it - b * 768, g = rem0 >> 8, rem = rem0 & 255, hh = rem & 3, rq = rem >> 2;
;     const int dl = 2 * g, dil = 1 << dl, r = rq & (dil - 1), qb = rq >> dl;
;     const float slope = exp2f(-8.0f * (float)(g * 4 + hh + 1) / 12.0f);
;     LAS bf16_t* Kl = (LAS bf16_t*)(lds + ATT_KL); LAS bf16_t* Vt = (LAS bf16_t*)(lds + ATT_VT); LAS bf16_t* Pw = (LAS bf16_t*)(lds + ATT_PW + wave * ATT_PW_WAVE);
;     const int colk = AW + g * 256 + hh * 64;
; #pragma unroll
;     for (int pp = 0; pp < 4; ++pp) {
;         const int p = tid + pp * NTHREADS, j = p >> 3, pc = p & 7, si = qb * 128 - 128 + j;
;         u32x4 kv = (u32x4){0u, 0u, 0u, 0u}, vv = (u32x4){0u, 0u, 0u, 0u};
;         if (si >= 0) { const bf16_t* kp = qkvb + (size_t)(b * SEQ + si * dil + r) * NQKV + colk + pc * 8; kv = *(const u32x4*)kp; vv = *(const u32x4*)(kp + AW); }
;         *(LAS u32x4*)(Kl + j * KL_PITCH + pc * 8) = kv;
;         LAS bf16_t* vd = Vt + (pc * 8) * VT_PITCH + ((((j >> 3) ^ pc) << 3) | (j & 7));
;         vd[0 * VT_PITCH] = (bf16_t)(vv.x & 0xffffu); vd[1 * VT_PITCH] = (bf16_t)(vv.x >> 16); vd[2 * VT_PITCH] = (bf16_t)(vv.y & 0xffffu); vd[3 * VT_PITCH] = (bf16_t)(vv.y >> 16);
;         vd[4 * VT_PITCH] = (bf16_t)(vv.z & 0xffffu); vd[5 * VT_PITCH] = (bf16_t)(vv.z >> 16); vd[6 * VT_PITCH] = (bf16_t)(vv.w & 0xffffu); vd[7 * VT_PITCH] = (bf16_t)(vv.w >> 16);
;     }
;     { const int d = tid >> 3, blk = 32 + (tid & 7); *(LAS u32x4*)(Vt + d * VT_PITCH + blk * 8) = (u32x4){0u, 0u, 0u, 0u}; }
;     const int ql = lane & 15, fq = lane >> 4;
;     const size_t qrow = (size_t)b * SEQ + (size_t)(qb * 128 + 16 * wave + ql) * dil + r;
;     const bf16_t* qp = qkvb + qrow * NQKV + g * 256 + hh * 64;
;     const bf16x8 q0 = *(const bf16x8*)(qp + 8 * fq), q1 = *(const bf16x8*)(qp + 32 + 8 * fq);
;     __syncthreads();
.LBB0_633:
	s_mul_hi_i32 s4, s76, 0x2aaaaaab
	s_lshr_b32 s6, s4, 31
	s_lshr_b32 s4, s4, 8
	s_add_i32 s4, s4, s6
	s_mulk_i32 s4, 0x600
	s_sub_i32 s4, s76, s4
	s_mul_i32 s6, s4, 0x2aab
	s_lshr_b32 s7, s6, 31
	s_ashr_i32 s30, s6, 23
	s_add_i32 s30, s30, s7
	s_mul_i32 s6, s30, 0xfffffd00
	s_add_i32 s6, s6, s4
	s_ashr_i32 s37, s6, 8
	s_and_b32 s77, s4, 3
	s_bfe_u32 s7, s4, 0x60002
	s_lshl_b32 s4, s37, 1
	s_lshl_b32 s26, -1, s4
	s_lshr_b32 s68, s7, s4
	s_and_b32 s80, s6, 0xffffff00
	s_andn2_b32 s28, s7, s26
	s_lshl_b32 s26, s77, 6
	s_lshl_b32 s31, s68, 7
	s_lshl_b32 s6, s30, 13
	s_ashr_i32 s81, s80, 31
	s_add_i32 s33, s31, 0xffffff80
	s_or_b32 s36, s28, s6
	s_or_b32 s6, s80, s26
	s_mov_b32 s7, s81
	s_cmp_eq_u32 s68, 0
	v_lshl_add_u64 v[8:9], s[6:7], 1, v[14:15]
	s_cbranch_scc1 .Lattp_zero01
	v_or_b32_e32 v200, s33, v22
	v_lshlrev_b32_e32 v200, s4, v200
	v_add_u32_e32 v200, s36, v200
	v_mad_i64_i32 v[200:201], s[6:7], v200, s42, v[8:9]
	global_load_dwordx4 v[206:209], v[200:201], off offset:1536
	global_load_dwordx4 v[210:213], v[200:201], off offset:3072
	v_add_u32_e32 v202, s33, v24
	v_lshlrev_b32_e32 v202, s4, v202
	v_add_u32_e32 v202, s36, v202
	v_mad_i64_i32 v[202:203], s[6:7], v202, s42, v[8:9]
	global_load_dwordx4 v[214:217], v[202:203], off offset:1536
	global_load_dwordx4 v[218:221], v[202:203], off offset:3072
	s_branch .Lattp_ld23
.Lattp_zero01:
	v_mov_b32_e32 v206, 0
	v_mov_b32_e32 v207, 0
	v_mov_b32_e32 v208, 0
	v_mov_b32_e32 v209, 0
	v_mov_b32_e32 v210, 0
	v_mov_b32_e32 v211, 0
	v_mov_b32_e32 v212, 0
	v_mov_b32_e32 v213, 0
	v_mov_b32_e32 v214, 0
	v_mov_b32_e32 v215, 0
	v_mov_b32_e32 v216, 0
	v_mov_b32_e32 v217, 0
	v_mov_b32_e32 v218, 0
	v_mov_b32_e32 v219, 0
	v_mov_b32_e32 v220, 0
	v_mov_b32_e32 v221, 0
.Lattp_ld23:
	v_add_u32_e32 v196, s33, v26
	v_lshlrev_b32_e32 v196, s4, v196
	v_add_u32_e32 v196, s36, v196
	v_mad_i64_i32 v[196:197], s[6:7], v196, s42, v[8:9]
	global_load_dwordx4 v[222:225], v[196:197], off offset:1536
	global_load_dwordx4 v[226:229], v[196:197], off offset:3072
	v_add_u32_e32 v198, s33, v28
	v_lshlrev_b32_e32 v198, s4, v198
	v_add_u32_e32 v198, s36, v198
	v_mad_i64_i32 v[198:199], s[6:7], v198, s42, v[8:9]
	global_load_dwordx4 v[230:233], v[198:199], off offset:1536
	global_load_dwordx4 v[234:237], v[198:199], off offset:3072
	s_waitcnt vmcnt(7)
	ds_write_b128 v98, v[206:209]
	s_waitcnt vmcnt(6)
	ds_write_b16 v23, v210 offset:36864
	ds_write_b16_d16_hi v23, v210 offset:37520
	ds_write_b16 v23, v211 offset:38176
	ds_write_b16_d16_hi v23, v211 offset:38832
	ds_write_b16 v23, v212 offset:39488
	ds_write_b16_d16_hi v23, v212 offset:40144
	ds_write_b16 v23, v213 offset:40800
	ds_write_b16_d16_hi v23, v213 offset:41456
	s_lshl_b32 s78, s37, 2
	s_waitcnt vmcnt(5)
	ds_write_b128 v99, v[214:217]
	s_waitcnt vmcnt(4)
	ds_write_b16 v25, v218 offset:36864
	ds_write_b16_d16_hi v25, v218 offset:37520
	ds_write_b16 v25, v219 offset:38176
	ds_write_b16_d16_hi v25, v219 offset:38832
	ds_write_b16 v25, v220 offset:39488
	ds_write_b16_d16_hi v25, v220 offset:40144
	ds_write_b16 v25, v221 offset:40800
	ds_write_b16_d16_hi v25, v221 offset:41456
	s_or_b32 s6, s77, s78
	s_add_i32 s6, s6, 1
	v_cvt_f32_i32_e32 v10, s6
	v_mul_f32_e32 v10, 0xc1000000, v10
	v_div_scale_f32 v11, s[6:7], s43, s43, v10
	v_rcp_f32_e32 v12, v11
	s_waitcnt vmcnt(3)
	ds_write_b128 v100, v[222:225]
	v_fma_f32 v17, -v11, v12, 1.0
	v_fmac_f32_e32 v12, v17, v12
	v_div_scale_f32 v17, vcc, v10, s43, v10
	v_mul_f32_e32 v18, v17, v12
	v_fma_f32 v19, -v11, v18, v17
	v_fmac_f32_e32 v18, v19, v12
	v_fma_f32 v11, -v11, v18, v17
	v_div_fmas_f32 v11, v11, v12, v18
	v_div_fixup_f32 v10, v11, s43, v10
	s_waitcnt vmcnt(2)
	ds_write_b16 v27, v226 offset:36864
	ds_write_b16_d16_hi v27, v226 offset:37520
	ds_write_b16 v27, v227 offset:38176
	ds_write_b16_d16_hi v27, v227 offset:38832
	ds_write_b16 v27, v228 offset:39488
	ds_write_b16_d16_hi v27, v228 offset:40144
	ds_write_b16 v27, v229 offset:40800
	ds_write_b16_d16_hi v27, v229 offset:41456
	s_mov_b32 s6, 0xc2fc0000
	v_cmp_gt_f32_e32 vcc, s6, v10
	s_and_b64 s[6:7], vcc, exec
	s_cselect_b32 s6, 0xffffffc0, 0
	s_add_i32 s31, s31, s69
	v_or_b32_e32 v12, s31, v161
	s_lshl_b64 s[80:81], s[80:81], 1
	s_waitcnt vmcnt(1)
	ds_write_b128 v101, v[230:233]
	s_waitcnt vmcnt(0)
	ds_write_b16 v29, v234 offset:36864
	ds_write_b16_d16_hi v29, v234 offset:37520
	ds_write_b16 v29, v235 offset:38176
	ds_write_b16_d16_hi v29, v235 offset:38832
	ds_write_b16 v29, v236 offset:39488
	ds_write_b16_d16_hi v29, v236 offset:40144
	ds_write_b16 v29, v237 offset:40800
	ds_write_b16_d16_hi v29, v237 offset:41456
	v_cndmask_b32_e32 v0, 0, v133, vcc
	v_add_f32_e32 v0, v10, v0
	v_exp_f32_e32 v0, v0
	ds_write_b128 v30, v[174:177] offset:37376
	v_ldexp_f32 v21, v0, s6
	s_sext_i32_i16 s6, s30
	s_ashr_i32 s7, s6, 31
	s_lshl_b64 s[6:7], s[6:7], 13
	v_lshlrev_b64 v[0:1], s4, v[12:13]
	s_or_b32 s6, s6, s28
	v_lshl_add_u64 v[18:19], s[6:7], 0, v[0:1]
	v_mov_b64_e32 v[0:1], s[24:25]
	v_mad_u64_u32 v[0:1], s[6:7], v18, s42, v[0:1]
	v_mov_b32_e32 v2, v1
	v_mad_u64_u32 v[2:3], s[6:7], v19, s42, v[2:3]
	v_mov_b32_e32 v1, v2
	v_lshl_add_u64 v[0:1], v[0:1], 0, s[80:81]
	s_lshl_b32 s28, s26, 1
	v_lshl_add_u64 v[0:1], v[0:1], 0, s[28:29]
	v_lshlrev_b32_e32 v12, 1, v154
	v_lshl_add_u64 v[4:5], v[0:1], 0, v[12:13]
	global_load_dwordx4 v[0:3], v[4:5], off
	s_nop 0
	global_load_dwordx4 v[4:7], v[4:5], off offset:64
	s_waitcnt lgkmcnt(0)
	s_barrier
; #define LAS __attribute__((address_space(3)))
; __device__ __forceinline__ void attn_prompt_item(LAS unsigned char* lds, const bf16_t* qkvb, bf16_t* og, float* lse, int it, int tid, int wave, int lane) {
;     ...
;     f32x4 sc[9]; float mx = -1e30f;
; #pragma unroll
;     for (int T = 0; T < 9; ++T) {
;         const LAS bf16_t* kr = Kl + (16 * (wave + T) + ql) * KL_PITCH + 8 * fq;
;         const bf16x8 a0 = *(const LAS bf16x8*)kr, a1 = *(const LAS bf16x8*)(kr + 32);
;         f32x4 acc = (f32x4){0.f, 0.f, 0.f, 0.f};
;         acc = __builtin_amdgcn_mfma_f32_16x16x32_bf16(a0, q0, acc, 0, 0, 0);
;         acc = __builtin_amdgcn_mfma_f32_16x16x32_bf16(a1, q1, acc, 0, 0, 0);
; #pragma unroll
;         for (int j = 0; j < 4; ++j) {
;             const int krel = 16 * T + 4 * fq + j, delta = 128 + ql - krel, ksub = qb * 128 - 128 + 16 * wave + krel;
;             const bool valid = (delta >= 0) && (delta <= 128) && (ksub >= 0);
;             const float s = valid ? acc[j] * 0.125f - slope * (float)(delta * dil) : -1e30f;
;             acc[j] = s; mx = fmaxf(mx, s); }
;         sc[T] = acc;
;     }
	ds_read_b128 v[8:11], v102
	ds_read_b128 v[136:139], v102 offset:64
	v_lshlrev_b32_e32 v12, s4, v31
	v_cvt_f32_u32_e32 v17, v12
	s_sub_i32 s26, 0x7f, s31
	v_cmp_lt_i32_e32 vcc, s26, v150
	s_and_b64 vcc, s[46:47], vcc
	s_mov_b32 s6, 0xf149f2ca
	s_waitcnt vmcnt(1) lgkmcnt(1)
	v_mfma_f32_16x16x32_bf16 v[8:11], v[8:11], v[0:3], 0
	s_waitcnt vmcnt(0) lgkmcnt(0)
	v_mfma_f32_16x16x32_bf16 v[8:11], v[136:139], v[4:7], v[8:11]
	s_nop 7
	v_mov_b32_e32 v20, v8
	v_pk_mul_f32 v[136:137], v[20:21], v[16:17]
	v_mov_b32_e32 v20, v9
	v_sub_f32_e32 v8, v136, v137
	v_cndmask_b32_e32 v12, v134, v8, vcc
	v_lshlrev_b32_e32 v8, s4, v32
	v_cvt_f32_u32_e32 v17, v8
	v_cmp_le_i32_e32 vcc, s26, v150
	s_and_b64 vcc, s[48:49], vcc
	v_pk_mul_f32 v[8:9], v[20:21], v[16:17]
	s_nop 0
	v_sub_f32_e32 v8, v8, v9
	v_cndmask_b32_e32 v136, v134, v8, vcc
	v_lshlrev_b32_e32 v8, s4, v33
	v_cvt_f32_u32_e32 v17, v8
	v_mov_b32_e32 v20, v10
	v_cmp_lt_i32_e32 vcc, s26, v151
	s_and_b64 vcc, s[50:51], vcc
	v_pk_mul_f32 v[8:9], v[20:21], v[16:17]
	v_mov_b32_e32 v20, v11
	v_sub_f32_e32 v8, v8, v9
	v_cndmask_b32_e32 v137, v134, v8, vcc
	v_lshlrev_b32_e32 v8, s4, v34
	v_cvt_f32_u32_e32 v17, v8
	v_cmp_lt_i32_e32 vcc, s26, v152
	s_and_b64 vcc, s[52:53], vcc
	v_max3_f32 v139, v12, s6, v136
	v_pk_mul_f32 v[8:9], v[20:21], v[16:17]
	v_lshlrev_b32_e32 v17, s4, v36
	v_sub_f32_e32 v8, v8, v9
	v_cndmask_b32_e32 v138, v134, v8, vcc
	ds_read_b128 v[8:11], v103
	ds_read_b128 v[140:143], v103 offset:64
	s_waitcnt lgkmcnt(1)
	v_mfma_f32_16x16x32_bf16 v[8:11], v[8:11], v[0:3], 0
	v_cvt_f32_u32_e32 v17, v17
	v_cmp_lt_i32_e32 vcc, s26, v35
	v_max3_f32 v139, v139, v137, v138
	s_waitcnt lgkmcnt(0)
	v_mfma_f32_16x16x32_bf16 v[8:11], v[140:143], v[4:7], v[8:11]
	s_nop 7
	v_mov_b32_e32 v20, v8
	v_pk_mul_f32 v[140:141], v[20:21], v[16:17]
	v_lshlrev_b32_e32 v17, s4, v38
	v_cvt_f32_u32_e32 v17, v17
	v_mov_b32_e32 v20, v9
	v_sub_f32_e32 v8, v140, v141
	v_cndmask_b32_e32 v8, v134, v8, vcc
	v_pk_mul_f32 v[140:141], v[20:21], v[16:17]
	v_lshlrev_b32_e32 v17, s4, v40
	v_cvt_f32_u32_e32 v17, v17
	v_mov_b32_e32 v20, v10
	v_cmp_lt_i32_e32 vcc, s26, v37
	v_sub_f32_e32 v9, v140, v141
	v_pk_mul_f32 v[140:141], v[20:21], v[16:17]
	v_cndmask_b32_e32 v9, v134, v9, vcc
	v_cmp_lt_i32_e32 vcc, s26, v39
	v_sub_f32_e32 v10, v140, v141
	v_max3_f32 v142, v139, v8, v9
	v_cndmask_b32_e32 v139, v134, v10, vcc
	v_lshlrev_b32_e32 v10, s4, v42
	v_cvt_f32_u32_e32 v17, v10
	v_mov_b32_e32 v20, v11
	v_cmp_lt_i32_e32 vcc, s26, v41
	v_pk_mul_f32 v[10:11], v[20:21], v[16:17]
	s_nop 0
	v_sub_f32_e32 v10, v10, v11
	v_cndmask_b32_e32 v10, v134, v10, vcc
	v_max3_f32 v148, v142, v139, v10
	ds_read_b128 v[140:143], v104
	ds_read_b128 v[144:147], v104 offset:64
	s_waitcnt lgkmcnt(1)
	v_mfma_f32_16x16x32_bf16 v[140:143], v[140:143], v[0:3], 0
	v_lshlrev_b32_e32 v11, s4, v44
	v_cvt_f32_u32_e32 v17, v11
	v_cmp_lt_i32_e32 vcc, s26, v43
	s_waitcnt lgkmcnt(0)
	v_mfma_f32_16x16x32_bf16 v[140:143], v[144:147], v[4:7], v[140:143]
	s_nop 7
	v_mov_b32_e32 v20, v140
	v_pk_mul_f32 v[144:145], v[20:21], v[16:17]
	v_lshlrev_b32_e32 v17, s4, v46
	v_cvt_f32_u32_e32 v17, v17
	v_mov_b32_e32 v20, v141
	v_sub_f32_e32 v11, v144, v145
	v_cndmask_b32_e32 v11, v134, v11, vcc
	v_pk_mul_f32 v[140:141], v[20:21], v[16:17]
	v_cmp_lt_i32_e32 vcc, s26, v45
	v_sub_f32_e32 v17, v140, v141
	v_mov_b32_e32 v20, v142
	v_cndmask_b32_e32 v140, v134, v17, vcc
	v_lshlrev_b32_e32 v17, s4, v48
	v_cvt_f32_u32_e32 v17, v17
	v_cmp_lt_i32_e32 vcc, s26, v47
	v_max3_f32 v146, v148, v11, v140
	v_pk_mul_f32 v[144:145], v[20:21], v[16:17]
	s_nop 0
	v_sub_f32_e32 v17, v144, v145
	v_cndmask_b32_e32 v142, v134, v17, vcc
	v_lshlrev_b32_e32 v17, s4, v50
	v_cvt_f32_u32_e32 v17, v17
	v_mov_b32_e32 v20, v143
	v_cmp_lt_i32_e32 vcc, s26, v49
	v_pk_mul_f32 v[144:145], v[20:21], v[16:17]
	s_nop 0
	v_sub_f32_e32 v17, v144, v145
	v_cndmask_b32_e32 v141, v134, v17, vcc
	v_max3_f32 v155, v146, v142, v141
	ds_read_b128 v[144:147], v105
	ds_read_b128 v[156:159], v105 offset:64
	s_waitcnt lgkmcnt(1)
	v_mfma_f32_16x16x32_bf16 v[144:147], v[144:147], v[0:3], 0
	v_lshlrev_b32_e32 v17, s4, v52
	v_cvt_f32_u32_e32 v17, v17
	v_cmp_lt_i32_e32 vcc, s26, v51
	s_waitcnt lgkmcnt(0)
	v_mfma_f32_16x16x32_bf16 v[144:147], v[156:159], v[4:7], v[144:147]
	ds_read_b128 v[156:159], v106
	ds_read_b128 v[166:169], v106 offset:64
	s_waitcnt lgkmcnt(1)
	v_mfma_f32_16x16x32_bf16 v[156:159], v[156:159], v[0:3], 0
	s_nop 3
	v_mov_b32_e32 v20, v144
	v_pk_mul_f32 v[148:149], v[20:21], v[16:17]
	v_mov_b32_e32 v20, v145
	v_sub_f32_e32 v17, v148, v149
	v_cndmask_b32_e32 v143, v134, v17, vcc
	v_lshlrev_b32_e32 v17, s4, v54
	v_cvt_f32_u32_e32 v17, v17
	v_cmp_lt_i32_e32 vcc, s26, v53
	s_waitcnt lgkmcnt(0)
	v_mfma_f32_16x16x32_bf16 v[156:159], v[166:169], v[4:7], v[156:159]
	v_mul_f32_e64 v144, v20, v16
	v_mul_f32_e64 v145, v21, v17
	v_sub_f32_e32 v17, v144, v145
	v_cndmask_b32_e32 v144, v134, v17, vcc
	v_lshlrev_b32_e32 v17, s4, v56
	v_cvt_f32_u32_e32 v17, v17
	v_mov_b32_e32 v20, v146
	v_cmp_lt_i32_e32 vcc, s26, v55
	v_max3_f32 v155, v155, v143, v144
	v_pk_mul_f32 v[148:149], v[20:21], v[16:17]
	v_mov_b32_e32 v20, v147
	v_sub_f32_e32 v17, v148, v149
	v_cndmask_b32_e32 v146, v134, v17, vcc
	v_lshlrev_b32_e32 v17, s4, v58
	v_cvt_f32_u32_e32 v17, v17
	v_cmp_lt_i32_e32 vcc, s26, v57
	v_pk_mul_f32 v[148:149], v[20:21], v[16:17]
	s_nop 0
	v_sub_f32_e32 v17, v148, v149
	v_cndmask_b32_e32 v145, v134, v17, vcc
	v_lshlrev_b32_e32 v17, s4, v60
	v_cvt_f32_u32_e32 v17, v17
	v_mov_b32_e32 v20, v156
	v_cmp_lt_i32_e32 vcc, s26, v59
	v_max3_f32 v155, v155, v146, v145
	v_pk_mul_f32 v[148:149], v[20:21], v[16:17]
	v_mov_b32_e32 v20, v157
	v_sub_f32_e32 v17, v148, v149
	v_cndmask_b32_e32 v147, v134, v17, vcc
	v_lshlrev_b32_e32 v17, s4, v62
	v_cvt_f32_u32_e32 v17, v17
	v_cmp_lt_i32_e32 vcc, s26, v61
	v_pk_mul_f32 v[148:149], v[20:21], v[16:17]
	s_nop 0
	v_sub_f32_e32 v17, v148, v149
	v_cndmask_b32_e32 v148, v134, v17, vcc
	v_lshlrev_b32_e32 v17, s4, v64
	v_cvt_f32_u32_e32 v17, v17
	v_mov_b32_e32 v20, v158
	v_cmp_lt_i32_e32 vcc, s26, v63
	v_max3_f32 v163, v155, v147, v148
	v_pk_mul_f32 v[156:157], v[20:21], v[16:17]
	v_mov_b32_e32 v20, v159
	v_sub_f32_e32 v17, v156, v157
	v_cndmask_b32_e32 v155, v134, v17, vcc
	v_lshlrev_b32_e32 v17, s4, v66
	v_cvt_f32_u32_e32 v17, v17
	v_cmp_lt_i32_e32 vcc, s26, v65
	v_pk_mul_f32 v[156:157], v[20:21], v[16:17]
	s_nop 0
	v_sub_f32_e32 v17, v156, v157
	ds_read_b128 v[156:159], v107
	ds_read_b128 v[166:169], v107 offset:64
	s_waitcnt lgkmcnt(1)
; #define LAS __attribute__((address_space(3)))
; __device__ __forceinline__ void attn_prompt_item(LAS unsigned char* lds, const bf16_t* qkvb, bf16_t* og, float* lse, int it, int tid, int wave, int lane) {
;     ...
;     for (int T = 0; T < 9; ++T) {
;         const LAS bf16_t* kr = Kl + (16 * (wave + T) + ql) * KL_PITCH + 8 * fq;
;         const bf16x8 a0 = *(const LAS bf16x8*)kr, a1 = *(const LAS bf16x8*)(kr + 32);
;         f32x4 acc = (f32x4){0.f, 0.f, 0.f, 0.f};
;         acc = __builtin_amdgcn_mfma_f32_16x16x32_bf16(a0, q0, acc, 0, 0, 0);
;         acc = __builtin_amdgcn_mfma_f32_16x16x32_bf16(a1, q1, acc, 0, 0, 0);
; #pragma unroll
;         for (int j = 0; j < 4; ++j) {
;             const int krel = 16 * T + 4 * fq + j, delta = 128 + ql - krel, ksub = qb * 128 - 128 + 16 * wave + krel;
;             const bool valid = (delta >= 0) && (delta <= 128) && (ksub >= 0);
;             const float s = valid ? acc[j] * 0.125f - slope * (float)(delta * dil) : -1e30f;
;             acc[j] = s; mx = fmaxf(mx, s); }
;         sc[T] = acc;
;     }
;     mx = fmaxf(mx, __shfl_xor(mx, 16)); mx = fmaxf(mx, __shfl_xor(mx, 32));
	v_mfma_f32_16x16x32_bf16 v[156:159], v[156:159], v[0:3], 0
	v_cndmask_b32_e32 v149, v134, v17, vcc
	v_lshlrev_b32_e32 v17, s4, v68
	v_cvt_f32_u32_e32 v17, v17
	s_waitcnt lgkmcnt(0)
	v_mfma_f32_16x16x32_bf16 v[166:169], v[166:169], v[4:7], v[156:159]
	v_cmp_lt_i32_e32 vcc, s26, v67
	v_max3_f32 v163, v163, v155, v149
	s_nop 5
	v_mov_b32_e32 v20, v166
	v_pk_mul_f32 v[156:157], v[20:21], v[16:17]
	v_mov_b32_e32 v20, v167
	v_sub_f32_e32 v17, v156, v157
	v_cndmask_b32_e32 v156, v134, v17, vcc
	v_lshlrev_b32_e32 v17, s4, v70
	v_cvt_f32_u32_e32 v17, v17
	v_cmp_lt_i32_e32 vcc, s26, v69
	v_pk_mul_f32 v[158:159], v[20:21], v[16:17]
	s_nop 0
	v_sub_f32_e32 v17, v158, v159
	v_cndmask_b32_e32 v157, v134, v17, vcc
	v_lshlrev_b32_e32 v17, s4, v72
	v_cvt_f32_u32_e32 v17, v17
	v_mov_b32_e32 v20, v168
	v_cmp_lt_i32_e32 vcc, s26, v71
	v_max3_f32 v163, v163, v156, v157
	v_pk_mul_f32 v[158:159], v[20:21], v[16:17]
	v_mov_b32_e32 v20, v169
	v_sub_f32_e32 v17, v158, v159
	v_cndmask_b32_e32 v159, v134, v17, vcc
	v_lshlrev_b32_e32 v17, s4, v74
	v_cvt_f32_u32_e32 v17, v17
	v_cmp_lt_i32_e32 vcc, s26, v73
	v_pk_mul_f32 v[166:167], v[20:21], v[16:17]
	s_nop 0
	v_sub_f32_e32 v17, v166, v167
	ds_read_b128 v[166:169], v108
	ds_read_b128 v[178:181], v108 offset:64
	s_waitcnt lgkmcnt(1)
	v_mfma_f32_16x16x32_bf16 v[166:169], v[166:169], v[0:3], 0
	v_cndmask_b32_e32 v158, v134, v17, vcc
	v_lshlrev_b32_e32 v17, s4, v76
	v_cvt_f32_u32_e32 v17, v17
	s_waitcnt lgkmcnt(0)
	v_mfma_f32_16x16x32_bf16 v[166:169], v[178:181], v[4:7], v[166:169]
	v_cmp_lt_i32_e32 vcc, s26, v75
	v_max3_f32 v171, v163, v159, v158
	ds_read_b128 v[178:181], v109
	ds_read_b128 v[182:185], v109 offset:64
	s_waitcnt lgkmcnt(1)
	v_mfma_f32_16x16x32_bf16 v[178:181], v[178:181], v[0:3], 0
	s_nop 1
	v_mov_b32_e32 v20, v166
	v_pk_mul_f32 v[172:173], v[20:21], v[16:17]
	v_mov_b32_e32 v20, v167
	v_sub_f32_e32 v17, v172, v173
	v_cndmask_b32_e32 v163, v134, v17, vcc
	v_lshlrev_b32_e32 v17, s4, v78
	v_cvt_f32_u32_e32 v17, v17
	v_cmp_lt_i32_e32 vcc, s26, v77
	s_waitcnt lgkmcnt(0)
	v_mfma_f32_16x16x32_bf16 v[178:181], v[182:185], v[4:7], v[178:181]
	v_mul_f32_e64 v166, v20, v16
	v_mul_f32_e64 v167, v21, v17
	v_sub_f32_e32 v17, v166, v167
	v_cndmask_b32_e32 v166, v134, v17, vcc
	v_lshlrev_b32_e32 v17, s4, v80
	v_cvt_f32_u32_e32 v17, v17
	v_mov_b32_e32 v20, v168
	v_cmp_lt_i32_e32 vcc, s26, v79
	v_max3_f32 v171, v171, v163, v166
	v_pk_mul_f32 v[172:173], v[20:21], v[16:17]
	v_mov_b32_e32 v20, v169
	v_sub_f32_e32 v17, v172, v173
	v_cndmask_b32_e32 v168, v134, v17, vcc
	v_lshlrev_b32_e32 v17, s4, v82
	v_cvt_f32_u32_e32 v17, v17
	v_cmp_lt_i32_e32 vcc, s26, v81
	v_pk_mul_f32 v[172:173], v[20:21], v[16:17]
	s_nop 0
	v_sub_f32_e32 v17, v172, v173
	v_cndmask_b32_e32 v167, v134, v17, vcc
	v_lshlrev_b32_e32 v17, s4, v84
	v_cvt_f32_u32_e32 v17, v17
	v_mov_b32_e32 v20, v178
	v_cmp_lt_i32_e32 vcc, s26, v83
	v_max3_f32 v186, v171, v168, v167
	v_pk_mul_f32 v[172:173], v[20:21], v[16:17]
	v_mov_b32_e32 v20, v179
	v_sub_f32_e32 v17, v172, v173
	v_cndmask_b32_e32 v169, v134, v17, vcc
	v_lshlrev_b32_e32 v17, s4, v86
	v_cvt_f32_u32_e32 v17, v17
	v_cmp_lt_i32_e32 vcc, s26, v85
	v_pk_mul_f32 v[172:173], v[20:21], v[16:17]
	s_nop 0
	v_sub_f32_e32 v17, v172, v173
	v_cndmask_b32_e32 v171, v134, v17, vcc
	v_lshlrev_b32_e32 v17, s4, v88
	v_cvt_f32_u32_e32 v17, v17
	v_mov_b32_e32 v20, v180
	v_cmp_lt_i32_e32 vcc, s26, v87
	v_max3_f32 v182, v186, v169, v171
	v_pk_mul_f32 v[172:173], v[20:21], v[16:17]
	v_mov_b32_e32 v20, v181
	v_sub_f32_e32 v17, v172, v173
	v_cndmask_b32_e32 v173, v134, v17, vcc
	v_lshlrev_b32_e32 v17, s4, v90
	v_cvt_f32_u32_e32 v17, v17
	v_cmp_lt_i32_e32 vcc, s26, v89
	v_pk_mul_f32 v[178:179], v[20:21], v[16:17]
	s_nop 0
	v_sub_f32_e32 v17, v178, v179
	v_cndmask_b32_e32 v172, v134, v17, vcc
	v_max3_f32 v186, v182, v173, v172
	ds_read_b128 v[178:181], v110
	ds_read_b128 v[182:185], v110 offset:64
	s_waitcnt lgkmcnt(1)
	v_mfma_f32_16x16x32_bf16 v[0:3], v[178:181], v[0:3], 0
	v_cmp_lt_f32_e32 vcc, s67, v12
	s_waitcnt lgkmcnt(0)
	v_mfma_f32_16x16x32_bf16 v[2:5], v[182:185], v[4:7], v[0:3]
	s_nop 4
	v_lshlrev_b32_e32 v0, s4, v91
	v_cvt_f32_i32_e32 v17, v0
	s_nop 0
	v_mov_b32_e32 v20, v2
	v_pk_mul_f32 v[0:1], v[20:21], v[16:17]
	s_nop 0
	v_sub_f32_e32 v0, v0, v1
	v_lshlrev_b32_e32 v1, s4, v92
	v_cvt_f32_i32_e32 v17, v1
	v_mov_b32_e32 v20, v3
	v_cndmask_b32_e64 v0, v134, v0, s[54:55]
	v_pk_mul_f32 v[2:3], v[20:21], v[16:17]
	s_nop 0
	v_sub_f32_e32 v1, v2, v3
	v_lshlrev_b32_e32 v2, s4, v93
	v_cvt_f32_i32_e32 v17, v2
	v_mov_b32_e32 v20, v4
	v_cndmask_b32_e64 v1, v134, v1, s[56:57]
	v_max3_f32 v6, v186, v0, v1
	v_pk_mul_f32 v[2:3], v[20:21], v[16:17]
	v_mov_b32_e32 v20, v5
	v_sub_f32_e32 v2, v2, v3
	v_cndmask_b32_e64 v3, v134, v2, s[58:59]
	v_lshlrev_b32_e32 v2, s4, v94
	v_cvt_f32_i32_e32 v17, v2
	v_pk_mul_f32 v[4:5], v[20:21], v[16:17]
	s_nop 0
	v_sub_f32_e32 v2, v4, v5
	v_cndmask_b32_e64 v4, v134, v2, s[60:61]
	v_max3_f32 v2, v6, v3, v4
	ds_bpermute_b32 v5, v96, v2
	s_waitcnt lgkmcnt(0)
	v_max_f32_e32 v5, v5, v5
	v_max_f32_e32 v2, v2, v5
	ds_bpermute_b32 v5, v97, v2
	s_waitcnt lgkmcnt(0)
; __device__ __forceinline__ unsigned cvt_pk_bf16(float lo, float hi) { unsigned r; asm volatile("v_cvt_pk_bf16_f32 %0, %1, %2" : "=v"(r) : "v"(lo), "v"(hi)); return r; }
; #define LAS __attribute__((address_space(3)))
; __device__ __forceinline__ void attn_prompt_item(LAS unsigned char* lds, const bf16_t* qkvb, bf16_t* og, float* lse, int it, int tid, int wave, int lane) {
;     ...
;     mx = fmaxf(mx, __shfl_xor(mx, 16)); mx = fmaxf(mx, __shfl_xor(mx, 32));
;     float den = 0.f;
; #pragma unroll
;     for (int T = 0; T < 9; ++T) {
;         f32x4 p;
; #pragma unroll
;         for (int j = 0; j < 4; ++j) { p[j] = sc[T][j] > -1e29f ? __expf(sc[T][j] - mx) : 0.f; den += p[j]; }
;         u32x2 w; w.x = cvt_pk_bf16(p[0], p[1]); w.y = cvt_pk_bf16(p[2], p[3]);
;         *(LAS u32x2*)(Pw + ql * PW_PITCH + 16 * T + 4 * fq) = w;
;     }
	v_max_f32_e32 v5, v5, v5
	v_max_f32_e32 v2, v2, v5
	v_sub_f32_e32 v5, v12, v2
	v_mul_f32_e32 v5, 0x3fb8aa3b, v5
	v_sub_f32_e32 v7, v136, v2
	v_exp_f32_e32 v5, v5
	v_mul_f32_e32 v7, 0x3fb8aa3b, v7
	v_sub_f32_e32 v12, v137, v2
	v_exp_f32_e32 v7, v7
	v_mul_f32_e32 v12, 0x3fb8aa3b, v12
	v_sub_f32_e32 v17, v138, v2
	v_exp_f32_e32 v12, v12
	v_mul_f32_e32 v17, 0x3fb8aa3b, v17
	v_exp_f32_e32 v17, v17
	v_cndmask_b32_e32 v5, 0, v5, vcc
	v_cmp_lt_f32_e32 vcc, s67, v136
	v_add_f32_e32 v6, 0, v5
	s_nop 0
	v_cndmask_b32_e32 v7, 0, v7, vcc
	v_cmp_lt_f32_e32 vcc, s67, v137
	v_add_f32_e32 v6, v7, v6
	s_nop 0
	v_cndmask_b32_e32 v12, 0, v12, vcc
	v_cmp_lt_f32_e32 vcc, s67, v138
	v_add_f32_e32 v6, v12, v6
	s_nop 0
	v_cndmask_b32_e32 v17, 0, v17, vcc
	v_add_f32_e32 v20, v17, v6
	v_cvt_pk_bf16_f32 v6, v5, v7
	v_sub_f32_e32 v5, v8, v2
	v_mul_f32_e32 v5, 0x3fb8aa3b, v5
	v_exp_f32_e32 v5, v5
	v_cvt_pk_bf16_f32 v7, v12, v17
	ds_write_b64 v95, v[6:7]
	v_sub_f32_e32 v7, v9, v2
	v_cmp_lt_f32_e32 vcc, s67, v8
	v_mul_f32_e32 v7, 0x3fb8aa3b, v7
	v_sub_f32_e32 v8, v139, v2
	v_cndmask_b32_e32 v5, 0, v5, vcc
	v_cmp_lt_f32_e32 vcc, s67, v9
	v_exp_f32_e32 v7, v7
	v_mul_f32_e32 v8, 0x3fb8aa3b, v8
	v_sub_f32_e32 v9, v10, v2
	v_exp_f32_e32 v8, v8
	v_mul_f32_e32 v9, 0x3fb8aa3b, v9
	v_exp_f32_e32 v9, v9
	v_add_f32_e32 v6, v5, v20
	v_cndmask_b32_e32 v7, 0, v7, vcc
	v_cmp_lt_f32_e32 vcc, s67, v139
	v_add_f32_e32 v6, v7, v6
	v_mov_b32_e32 v12, v13
	v_cndmask_b32_e32 v8, 0, v8, vcc
	v_cmp_lt_f32_e32 vcc, s67, v10
	v_add_f32_e32 v6, v8, v6
	s_nop 0
	v_cndmask_b32_e32 v9, 0, v9, vcc
	v_add_f32_e32 v10, v9, v6
	v_cvt_pk_bf16_f32 v6, v5, v7
	v_cvt_pk_bf16_f32 v7, v8, v9
	v_sub_f32_e32 v5, v11, v2
	ds_write_b64 v95, v[6:7] offset:32
	v_mul_f32_e32 v5, 0x3fb8aa3b, v5
	v_sub_f32_e32 v7, v140, v2
	v_exp_f32_e32 v5, v5
	v_mul_f32_e32 v7, 0x3fb8aa3b, v7
	v_sub_f32_e32 v8, v142, v2
	v_exp_f32_e32 v7, v7
	v_mul_f32_e32 v8, 0x3fb8aa3b, v8
	v_sub_f32_e32 v9, v141, v2
	v_exp_f32_e32 v8, v8
	v_mul_f32_e32 v9, 0x3fb8aa3b, v9
	v_cmp_lt_f32_e32 vcc, s67, v11
	v_exp_f32_e32 v9, v9
	s_nop 0
	v_cndmask_b32_e32 v5, 0, v5, vcc
	v_cmp_lt_f32_e32 vcc, s67, v140
	v_add_f32_e32 v6, v5, v10
	s_nop 0
	v_cndmask_b32_e32 v7, 0, v7, vcc
	v_cmp_lt_f32_e32 vcc, s67, v142
	v_add_f32_e32 v6, v7, v6
	s_nop 0
	v_cndmask_b32_e32 v8, 0, v8, vcc
	v_cmp_lt_f32_e32 vcc, s67, v141
	v_add_f32_e32 v6, v8, v6
	s_nop 0
	v_cndmask_b32_e32 v9, 0, v9, vcc
	v_add_f32_e32 v10, v9, v6
	v_cvt_pk_bf16_f32 v6, v5, v7
	v_cvt_pk_bf16_f32 v7, v8, v9
	v_sub_f32_e32 v5, v143, v2
	ds_write_b64 v95, v[6:7] offset:64
	v_mul_f32_e32 v5, 0x3fb8aa3b, v5
	v_sub_f32_e32 v7, v144, v2
	v_exp_f32_e32 v5, v5
	v_mul_f32_e32 v7, 0x3fb8aa3b, v7
	v_sub_f32_e32 v8, v146, v2
	v_exp_f32_e32 v7, v7
	v_mul_f32_e32 v8, 0x3fb8aa3b, v8
	v_sub_f32_e32 v9, v145, v2
	v_exp_f32_e32 v8, v8
	v_mul_f32_e32 v9, 0x3fb8aa3b, v9
	v_cmp_lt_f32_e32 vcc, s67, v143
	v_exp_f32_e32 v9, v9
	s_nop 0
	v_cndmask_b32_e32 v5, 0, v5, vcc
	v_cmp_lt_f32_e32 vcc, s67, v144
	v_add_f32_e32 v6, v5, v10
	s_nop 0
	v_cndmask_b32_e32 v7, 0, v7, vcc
	v_cmp_lt_f32_e32 vcc, s67, v146
	v_add_f32_e32 v6, v7, v6
	s_nop 0
	v_cndmask_b32_e32 v8, 0, v8, vcc
	v_cmp_lt_f32_e32 vcc, s67, v145
	v_add_f32_e32 v6, v8, v6
	s_nop 0
	v_cndmask_b32_e32 v9, 0, v9, vcc
	v_add_f32_e32 v10, v9, v6
	v_cvt_pk_bf16_f32 v6, v5, v7
	v_cvt_pk_bf16_f32 v7, v8, v9
	v_sub_f32_e32 v5, v147, v2
	ds_write_b64 v95, v[6:7] offset:96
	v_mul_f32_e32 v5, 0x3fb8aa3b, v5
	v_sub_f32_e32 v7, v148, v2
	v_exp_f32_e32 v5, v5
	v_mul_f32_e32 v7, 0x3fb8aa3b, v7
	v_sub_f32_e32 v8, v155, v2
	v_exp_f32_e32 v7, v7
	v_mul_f32_e32 v8, 0x3fb8aa3b, v8
	v_sub_f32_e32 v9, v149, v2
	v_exp_f32_e32 v8, v8
	v_mul_f32_e32 v9, 0x3fb8aa3b, v9
	v_cmp_lt_f32_e32 vcc, s67, v147
	v_exp_f32_e32 v9, v9
	s_nop 0
	v_cndmask_b32_e32 v5, 0, v5, vcc
	v_cmp_lt_f32_e32 vcc, s67, v148
	v_add_f32_e32 v6, v5, v10
	s_nop 0
	v_cndmask_b32_e32 v7, 0, v7, vcc
	v_cmp_lt_f32_e32 vcc, s67, v155
	v_add_f32_e32 v6, v7, v6
	s_nop 0
	v_cndmask_b32_e32 v8, 0, v8, vcc
	v_cmp_lt_f32_e32 vcc, s67, v149
	v_add_f32_e32 v6, v8, v6
	s_nop 0
	v_cndmask_b32_e32 v9, 0, v9, vcc
	v_add_f32_e32 v10, v9, v6
	v_cvt_pk_bf16_f32 v6, v5, v7
	v_cvt_pk_bf16_f32 v7, v8, v9
	v_sub_f32_e32 v5, v156, v2
	ds_write_b64 v95, v[6:7] offset:128
	v_mul_f32_e32 v5, 0x3fb8aa3b, v5
	v_sub_f32_e32 v7, v157, v2
	v_exp_f32_e32 v5, v5
	v_mul_f32_e32 v7, 0x3fb8aa3b, v7
	v_sub_f32_e32 v8, v159, v2
	v_exp_f32_e32 v7, v7
	v_mul_f32_e32 v8, 0x3fb8aa3b, v8
	v_sub_f32_e32 v9, v158, v2
	v_exp_f32_e32 v8, v8
	v_mul_f32_e32 v9, 0x3fb8aa3b, v9
	v_cmp_lt_f32_e32 vcc, s67, v156
	v_exp_f32_e32 v9, v9
	s_nop 0
	v_cndmask_b32_e32 v5, 0, v5, vcc
	v_cmp_lt_f32_e32 vcc, s67, v157
	v_add_f32_e32 v6, v5, v10
	s_nop 0
	v_cndmask_b32_e32 v7, 0, v7, vcc
	v_cmp_lt_f32_e32 vcc, s67, v159
	v_add_f32_e32 v6, v7, v6
	s_nop 0
	v_cndmask_b32_e32 v8, 0, v8, vcc
	v_cmp_lt_f32_e32 vcc, s67, v158
	v_add_f32_e32 v6, v8, v6
	s_nop 0
	v_cndmask_b32_e32 v9, 0, v9, vcc
	v_add_f32_e32 v10, v9, v6
	v_cvt_pk_bf16_f32 v6, v5, v7
	v_cvt_pk_bf16_f32 v7, v8, v9
	v_sub_f32_e32 v5, v163, v2
	ds_write_b64 v95, v[6:7] offset:160
	v_mul_f32_e32 v5, 0x3fb8aa3b, v5
	v_sub_f32_e32 v7, v166, v2
	v_exp_f32_e32 v5, v5
	v_mul_f32_e32 v7, 0x3fb8aa3b, v7
	v_sub_f32_e32 v8, v168, v2
	v_exp_f32_e32 v7, v7
	v_mul_f32_e32 v8, 0x3fb8aa3b, v8
	v_sub_f32_e32 v9, v167, v2
	v_exp_f32_e32 v8, v8
	v_mul_f32_e32 v9, 0x3fb8aa3b, v9
	v_cmp_lt_f32_e32 vcc, s67, v163
	v_exp_f32_e32 v9, v9
	s_nop 0
	v_cndmask_b32_e32 v5, 0, v5, vcc
	v_cmp_lt_f32_e32 vcc, s67, v166
	v_add_f32_e32 v6, v5, v10
	s_nop 0
	v_cndmask_b32_e32 v7, 0, v7, vcc
	v_cmp_lt_f32_e32 vcc, s67, v168
	v_add_f32_e32 v6, v7, v6
	s_nop 0
; __device__ __forceinline__ unsigned cvt_pk_bf16(float lo, float hi) { unsigned r; asm volatile("v_cvt_pk_bf16_f32 %0, %1, %2" : "=v"(r) : "v"(lo), "v"(hi)); return r; }
; #define LAS __attribute__((address_space(3)))
; __device__ __forceinline__ void attn_prompt_item(LAS unsigned char* lds, const bf16_t* qkvb, bf16_t* og, float* lse, int it, int tid, int wave, int lane) {
;     ...
;     *(LAS u32x2*)(Pw + ql * PW_PITCH + 144 + 4 * fq) = (u32x2){0u, 0u};
;     den += __shfl_xor(den, 16); den += __shfl_xor(den, 32);
;     const float inv = 1.0f / den;
;     __syncthreads();
;     bf16_t* op = og + qrow * AW + g * 256 + hh * 64 + 4 * fq;
; #pragma unroll
;     for (int dt = 0; dt < 4; ++dt) {
;         f32x4 o = (f32x4){0.f, 0.f, 0.f, 0.f};
; #pragma unroll
;         for (int ks = 0; ks < 5; ++ks) {
;             const bf16x8 av = *(const LAS bf16x8*)(Vt + (16 * dt + ql) * VT_PITCH + (((2 * wave + 4 * ks + fq) ^ ((2 * dt + (ql >> 3)) & 7)) << 3));
;             const bf16x8 bp = *(const LAS bf16x8*)(Pw + ql * PW_PITCH + 32 * ks + 8 * fq);
;             o = __builtin_amdgcn_mfma_f32_16x16x32_bf16(av, bp, o, 0, 0, 0); }
;         u32x2 w; w.x = cvt_pk_bf16(o[0] * inv, o[1] * inv); w.y = cvt_pk_bf16(o[2] * inv, o[3] * inv);
;         *(u32x2*)(op + 16 * dt) = w;
;     }
;     if (fq == 0) lse[qrow * 12 + g * 4 + hh] = mx + __logf(den);
	v_cndmask_b32_e32 v8, 0, v8, vcc
	v_cmp_lt_f32_e32 vcc, s67, v167
	v_add_f32_e32 v6, v8, v6
	s_nop 0
	v_cndmask_b32_e32 v9, 0, v9, vcc
	v_add_f32_e32 v10, v9, v6
	v_cvt_pk_bf16_f32 v6, v5, v7
	v_cvt_pk_bf16_f32 v7, v8, v9
	v_sub_f32_e32 v5, v169, v2
	ds_write_b64 v95, v[6:7] offset:192
	v_mul_f32_e32 v5, 0x3fb8aa3b, v5
	v_sub_f32_e32 v7, v171, v2
	v_exp_f32_e32 v5, v5
	v_mul_f32_e32 v7, 0x3fb8aa3b, v7
	v_sub_f32_e32 v8, v173, v2
	v_exp_f32_e32 v7, v7
	v_mul_f32_e32 v8, 0x3fb8aa3b, v8
	v_sub_f32_e32 v9, v172, v2
	v_exp_f32_e32 v8, v8
	v_mul_f32_e32 v9, 0x3fb8aa3b, v9
	v_cmp_lt_f32_e32 vcc, s67, v169
	v_exp_f32_e32 v9, v9
	s_nop 0
	v_cndmask_b32_e32 v5, 0, v5, vcc
	v_cmp_lt_f32_e32 vcc, s67, v171
	v_add_f32_e32 v6, v5, v10
	s_nop 0
	v_cndmask_b32_e32 v7, 0, v7, vcc
	v_cmp_lt_f32_e32 vcc, s67, v173
	v_add_f32_e32 v6, v7, v6
	s_nop 0
	v_cndmask_b32_e32 v8, 0, v8, vcc
	v_cmp_lt_f32_e32 vcc, s67, v172
	v_add_f32_e32 v6, v8, v6
	s_nop 0
	v_cndmask_b32_e32 v9, 0, v9, vcc
	v_cmp_lt_f32_e32 vcc, s67, v0
	v_sub_f32_e32 v0, v0, v2
	v_mul_f32_e32 v0, 0x3fb8aa3b, v0
	v_exp_f32_e32 v0, v0
	v_add_f32_e32 v10, v9, v6
	v_cvt_pk_bf16_f32 v6, v5, v7
	v_cvt_pk_bf16_f32 v7, v8, v9
	v_cndmask_b32_e32 v0, 0, v0, vcc
	v_cmp_lt_f32_e32 vcc, s67, v1
	v_sub_f32_e32 v1, v1, v2
	v_mul_f32_e32 v1, 0x3fb8aa3b, v1
	v_exp_f32_e32 v1, v1
	v_add_f32_e32 v5, v0, v10
	ds_write_b64 v95, v[6:7] offset:224
	v_cndmask_b32_e32 v1, 0, v1, vcc
	v_cmp_lt_f32_e32 vcc, s67, v3
	v_sub_f32_e32 v3, v3, v2
	v_mul_f32_e32 v3, 0x3fb8aa3b, v3
	v_exp_f32_e32 v3, v3
	v_add_f32_e32 v5, v1, v5
	v_cvt_pk_bf16_f32 v0, v0, v1
	v_cndmask_b32_e32 v3, 0, v3, vcc
	v_cmp_lt_f32_e32 vcc, s67, v4
	v_sub_f32_e32 v4, v4, v2
	v_mul_f32_e32 v4, 0x3fb8aa3b, v4
	v_exp_f32_e32 v4, v4
	v_add_f32_e32 v5, v3, v5
	v_cndmask_b32_e32 v4, 0, v4, vcc
	v_add_f32_e32 v5, v4, v5
	v_cvt_pk_bf16_f32 v1, v3, v4
	ds_write2_b64 v95, v[0:1], v[12:13] offset0:32 offset1:36
	ds_bpermute_b32 v0, v96, v5
	s_waitcnt lgkmcnt(0)
	s_barrier
	v_lshlrev_b32_e32 v12, 1, v150
	v_add_f32_e32 v0, v5, v0
	ds_bpermute_b32 v1, v97, v0
	s_waitcnt lgkmcnt(0)
	v_add_f32_e32 v3, v0, v1
	v_div_scale_f32 v0, s[6:7], v3, v3, 1.0
	v_rcp_f32_e32 v1, v0
	s_nop 0
	v_fma_f32 v4, -v0, v1, 1.0
	v_fmac_f32_e32 v1, v4, v1
	v_div_scale_f32 v4, vcc, 1.0, v3, 1.0
	v_mul_f32_e32 v5, v4, v1
	v_fma_f32 v6, -v0, v5, v4
	v_fmac_f32_e32 v5, v6, v1
	v_fma_f32 v0, -v0, v5, v4
	v_div_fmas_f32 v0, v0, v1, v5
	v_div_fixup_f32 v17, v0, v3, 1.0
	v_mov_b64_e32 v[0:1], s[34:35]
	v_mad_u64_u32 v[0:1], s[6:7], v18, s27, v[0:1]
	v_mov_b32_e32 v4, v1
	v_mad_u64_u32 v[4:5], s[6:7], v19, s27, v[4:5]
	v_mov_b32_e32 v1, v4
	ds_read_b128 v[4:7], v111 offset:36864
	v_lshl_add_u64 v[0:1], v[0:1], 0, s[80:81]
	v_lshl_add_u64 v[0:1], v[0:1], 0, s[28:29]
	v_lshl_add_u64 v[0:1], v[0:1], 0, v[12:13]
	v_add_u32_e32 v12, v95, v154
	ds_read_b128 v[8:11], v12
	s_waitcnt lgkmcnt(0)
	v_mfma_f32_16x16x32_bf16 v[4:7], v[4:7], v[8:11], 0
	ds_read_b128 v[8:11], v112 offset:36864
	ds_read_b128 v[136:139], v12 offset:64
	s_waitcnt lgkmcnt(0)
	v_mfma_f32_16x16x32_bf16 v[4:7], v[8:11], v[136:139], v[4:7]
	ds_read_b128 v[8:11], v113 offset:36864
	ds_read_b128 v[136:139], v12 offset:128
	s_waitcnt lgkmcnt(0)
	v_mfma_f32_16x16x32_bf16 v[4:7], v[8:11], v[136:139], v[4:7]
	ds_read_b128 v[8:11], v114 offset:36864
	ds_read_b128 v[136:139], v12 offset:192
	s_waitcnt lgkmcnt(0)
	v_mfma_f32_16x16x32_bf16 v[4:7], v[8:11], v[136:139], v[4:7]
	ds_read_b128 v[8:11], v115 offset:36864
	ds_read_b128 v[136:139], v12 offset:256
	s_waitcnt lgkmcnt(0)
	v_mfma_f32_16x16x32_bf16 v[4:7], v[8:11], v[136:139], v[4:7]
	s_nop 7
	v_mul_f32_e32 v4, v17, v4
	v_mul_f32_e32 v5, v17, v5
	v_cvt_pk_bf16_f32 v4, v4, v5
	v_mul_f32_e32 v5, v17, v6
	v_mul_f32_e32 v6, v17, v7
	v_cvt_pk_bf16_f32 v5, v5, v6
	global_store_dwordx2 v[0:1], v[4:5], off
	ds_read_b128 v[4:7], v116 offset:47360
	ds_read_b128 v[8:11], v12
	s_waitcnt lgkmcnt(0)
	v_mfma_f32_16x16x32_bf16 v[4:7], v[4:7], v[8:11], 0
	ds_read_b128 v[8:11], v117 offset:47360
	ds_read_b128 v[136:139], v12 offset:64
	s_waitcnt lgkmcnt(0)
	v_mfma_f32_16x16x32_bf16 v[4:7], v[8:11], v[136:139], v[4:7]
	ds_read_b128 v[8:11], v118 offset:47360
	ds_read_b128 v[136:139], v12 offset:128
	s_waitcnt lgkmcnt(0)
	v_mfma_f32_16x16x32_bf16 v[4:7], v[8:11], v[136:139], v[4:7]
	ds_read_b128 v[8:11], v119 offset:47360
	ds_read_b128 v[136:139], v12 offset:192
	s_waitcnt lgkmcnt(0)
	v_mfma_f32_16x16x32_bf16 v[4:7], v[8:11], v[136:139], v[4:7]
	ds_read_b128 v[8:11], v120 offset:47360
	ds_read_b128 v[136:139], v12 offset:256
	s_waitcnt lgkmcnt(0)
	v_mfma_f32_16x16x32_bf16 v[4:7], v[8:11], v[136:139], v[4:7]
	s_nop 7
	v_mul_f32_e32 v4, v17, v4
	v_mul_f32_e32 v5, v17, v5
	v_cvt_pk_bf16_f32 v4, v4, v5
	v_mul_f32_e32 v5, v17, v6
	v_mul_f32_e32 v6, v17, v7
	v_cvt_pk_bf16_f32 v5, v5, v6
	global_store_dwordx2 v[0:1], v[4:5], off offset:32
	ds_read_b128 v[4:7], v121 offset:57856
	ds_read_b128 v[8:11], v12
	s_waitcnt lgkmcnt(0)
	v_mfma_f32_16x16x32_bf16 v[4:7], v[4:7], v[8:11], 0
	ds_read_b128 v[8:11], v122 offset:57856
	ds_read_b128 v[136:139], v12 offset:64
	s_waitcnt lgkmcnt(0)
	v_mfma_f32_16x16x32_bf16 v[4:7], v[8:11], v[136:139], v[4:7]
	ds_read_b128 v[8:11], v123 offset:57856
	ds_read_b128 v[136:139], v12 offset:128
	s_waitcnt lgkmcnt(0)
	v_mfma_f32_16x16x32_bf16 v[4:7], v[8:11], v[136:139], v[4:7]
	ds_read_b128 v[8:11], v124 offset:57856
	ds_read_b128 v[136:139], v12 offset:192
	s_waitcnt lgkmcnt(0)
	v_mfma_f32_16x16x32_bf16 v[4:7], v[8:11], v[136:139], v[4:7]
	ds_read_b128 v[8:11], v125 offset:57856
	ds_read_b128 v[136:139], v12 offset:256
	s_waitcnt lgkmcnt(0)
	v_mfma_f32_16x16x32_bf16 v[4:7], v[8:11], v[136:139], v[4:7]
	s_nop 7
	v_mul_f32_e32 v4, v17, v4
	v_mul_f32_e32 v5, v17, v5
	v_cvt_pk_bf16_f32 v4, v4, v5
	v_mul_f32_e32 v5, v17, v6
	v_mul_f32_e32 v6, v17, v7
	v_cvt_pk_bf16_f32 v5, v5, v6
	global_store_dwordx2 v[0:1], v[4:5], off offset:64
	ds_read_b128 v[4:7], v126 offset:36864
	ds_read_b128 v[8:11], v12
	s_waitcnt lgkmcnt(0)
	v_mfma_f32_16x16x32_bf16 v[4:7], v[4:7], v[8:11], 0
	ds_read_b128 v[8:11], v127 offset:36864
	ds_read_b128 v[136:139], v12 offset:64
	s_waitcnt lgkmcnt(0)
	v_mfma_f32_16x16x32_bf16 v[4:7], v[8:11], v[136:139], v[4:7]
	ds_read_b128 v[8:11], v130 offset:36864
	ds_read_b128 v[136:139], v12 offset:128
	s_waitcnt lgkmcnt(0)
	v_mfma_f32_16x16x32_bf16 v[4:7], v[8:11], v[136:139], v[4:7]
	ds_read_b128 v[8:11], v131 offset:36864
	ds_read_b128 v[136:139], v12 offset:192
	s_waitcnt lgkmcnt(0)
	v_mfma_f32_16x16x32_bf16 v[4:7], v[8:11], v[136:139], v[4:7]
	ds_read_b128 v[8:11], v132 offset:36864
	ds_read_b128 v[136:139], v12 offset:256
	s_waitcnt lgkmcnt(0)
	v_mfma_f32_16x16x32_bf16 v[4:7], v[8:11], v[136:139], v[4:7]
	s_nop 7
	v_mul_f32_e32 v4, v17, v4
	v_mul_f32_e32 v5, v17, v5
	v_cvt_pk_bf16_f32 v4, v4, v5
	v_mul_f32_e32 v5, v17, v6
	v_mul_f32_e32 v6, v17, v7
	v_cvt_pk_bf16_f32 v5, v5, v6
	global_store_dwordx2 v[0:1], v[4:5], off offset:96
	s_and_saveexec_b64 s[80:81], s[72:73]
	s_cbranch_execz .LBB0_632
; __device__ __forceinline__ void attn_prompt_item(LAS unsigned char* lds, const bf16_t* qkvb, bf16_t* og, float* lse, int it, int tid, int wave, int lane) {
;     ...
;     if (fq == 0) lse[qrow * 12 + g * 4 + hh] = mx + __logf(den);
; __device__ __forceinline__ void attn_sample_item(const Args& a, const bf16_t* qkvb, bf16_t* og, float* lse, int it, int lane) {
;     const int t = it & 7, hh = (it >> 3) & 3, bg = it >> 5, b = bg / 3, g = bg - 3 * b;
;     const int W = 128 << (2 * g), dil = 1 << (2 * g);
;     const float slope = exp2f(-8.0f * (float)(g * 4 + hh + 1) / 12.0f);
;     const int row = MP + b * 8 + t;
;     const float* cache = a.in[2 + g] + (size_t)b * W * 512 + hh * 64;
;     const float* kvs = a.out + (g == 0 ? O_KVS0 : (g == 1 ? O_KVS1 : O_KVS2)) + (size_t)b * W * 512 + hh * 64;
;     const bf16_t* qp = qkvb + (size_t)row * NQKV + g * 256 + hh * 64;
;     float q[64];
; #pragma unroll
;     for (int i = 0; i < 8; ++i) { const u32x4 w = *(const u32x4*)(qp + 8 * i);
;         q[8 * i + 0] = __uint_as_float(w.x << 16); q[8 * i + 1] = __uint_as_float(w.x & 0xffff0000u); q[8 * i + 2] = __uint_as_float(w.y << 16); q[8 * i + 3] = __uint_as_float(w.y & 0xffff0000u);
;         q[8 * i + 4] = __uint_as_float(w.z << 16); q[8 * i + 5] = __uint_as_float(w.z & 0xffff0000u); q[8 * i + 6] = __uint_as_float(w.w << 16); q[8 * i + 7] = __uint_as_float(w.w & 0xffff0000u); }
;     float sc[3];
; #pragma unroll
;     for (int pass = 0; pass < 3; ++pass) {
;         const int j = lane + 64 * pass; const bool valid = j <= 128; const int jj = valid ? j : 128;
;         const int idx = W + t - jj * dil;
;         const float* kp = idx < W ? cache + (size_t)idx * 512 : kvs + (size_t)(idx - 8) * 512;
;         float dot = 0.f;
; #pragma unroll
	s_mov_b32 s4, 0x800000
	v_cmp_gt_f32_e32 vcc, s4, v3
	s_mov_b32 s4, 0x3f317217
	s_ashr_i32 s79, s78, 31
	v_cndmask_b32_e64 v0, 0, 32, vcc
	v_ldexp_f32 v0, v3, v0
	v_log_f32_e32 v0, v0
	v_cndmask_b32_e32 v1, 0, v135, vcc
	s_lshl_b32 s28, s77, 2
	v_mul_f32_e32 v3, 0x3f317217, v0
	v_fma_f32 v3, v0, s4, -v3
	v_fmac_f32_e32 v3, 0x3377d1cf, v0
	s_mov_b32 s4, 0x7f800000
	v_fmac_f32_e32 v3, 0x3f317217, v0
	v_cmp_lt_f32_e64 vcc, |v0|, s4
	s_nop 1
	v_cndmask_b32_e32 v0, v0, v3, vcc
	v_sub_f32_e32 v0, v0, v1
	v_add_f32_e32 v4, v2, v0
	v_mad_u64_u32 v[0:1], s[6:7], v18, 48, s[38:39]
	v_mov_b32_e32 v2, v1
	v_mad_u64_u32 v[2:3], s[6:7], v19, 48, v[2:3]
	v_mov_b32_e32 v1, v2
	v_lshl_add_u64 v[0:1], s[78:79], 2, v[0:1]
	v_lshl_add_u64 v[0:1], v[0:1], 0, s[28:29]
	global_store_dword v[0:1], v4, off
	s_branch .LBB0_632
.LBB0_640:
	v_writelane_b32 v243, s69, 7
	s_cmpk_gt_i32 s64, 0xbff
	v_readlane_b32 s68, v243, 59
	v_readlane_b32 s69, v243, 60
	s_cbranch_scc1 .LBB0_647
	v_lshlrev_b32_e32 v177, 2, v192
	v_mov_b32_e32 v178, 0
	v_xor_b32_e32 v171, 1, v192
	v_lshlrev_b32_e32 v171, 2, v171
	v_xor_b32_e32 v172, 2, v192
	v_lshlrev_b32_e32 v172, 2, v172
	v_xor_b32_e32 v173, 4, v192
	v_lshlrev_b32_e32 v173, 2, v173
	v_xor_b32_e32 v174, 8, v192
	v_lshlrev_b32_e32 v174, 2, v174
	v_xor_b32_e32 v175, 16, v192
	v_lshlrev_b32_e32 v175, 2, v175
	v_xor_b32_e32 v176, 32, v192
	v_lshlrev_b32_e32 v176, 2, v176
	s_mov_b32 s60, s64
.Latts_item:
	s_and_b32 s61, s60, 7
	s_bfe_u32 s4, s60, 0x20003
	s_lshr_b32 s6, s60, 5
	s_mul_hi_u32 s7, s6, 0x55555556
	s_mul_i32 s36, s7, 3
	s_sub_u32 s36, s6, s36
	s_lshl_b32 s67, s36, 1
	s_lshl_b32 s72, 0x80, s67
	s_add_u32 s72, s72, s61
	s_lshl_b32 s6, s36, 3
	s_add_u32 s6, s6, 0x10
	s_load_dwordx2 s[30:31], s[0:1], s6
	s_load_dwordx2 s[32:33], s[0:1], 0xc8
	s_load_dwordx2 s[80:81], s[0:1], 0xd0
	s_lshl_b32 s6, s36, 2
	s_add_u32 s6, s6, s4
	s_add_u32 s6, s6, 1
	v_cvt_f32_i32_e32 v191, s6
	v_mul_f32_e32 v191, 0xbf2aaaab, v191
	v_exp_f32_e32 v191, v191
	s_add_u32 s6, s67, 18
	s_lshl_b32 s6, s7, s6
	s_lshl_b32 s37, s4, 8
	s_add_u32 s37, s37, s6
	s_mov_b32 s6, 0x5390000
	s_cmp_eq_u32 s36, 0
	s_cselect_b32 s6, 0x4b90000, s6
	s_cmp_eq_u32 s36, 2
	s_cselect_b32 s6, 0x7390000, s6
	s_add_u32 s82, s37, s6
	s_sub_u32 s82, s82, 0x4000
	s_lshl_b32 s6, s7, 3
	s_add_u32 s6, s6, s61
	s_add_u32 s73, s6, 0x4000
	s_mul_i32 s6, s73, 0x900
	s_lshl_b32 s7, s36, 8
	s_add_u32 s6, s6, s7
	s_lshl_b32 s7, s4, 6
	s_add_u32 s6, s6, s7
	s_lshl_b32 s6, s6, 1
	s_add_u32 s6, s6, 0xaf80000
	v_readfirstlane_b32 s56, v191
	s_waitcnt lgkmcnt(0)
	s_add_u32 s30, s30, s37
	s_addc_u32 s31, s31, 0
	s_add_u32 s32, s32, s82
	s_addc_u32 s33, s33, 0
	s_add_u32 s80, s80, s6
	s_addc_u32 s81, s81, 0
	s_mov_b32 s82, s56
	s_load_dwordx8 s[40:47], s[80:81], 0x0
	s_load_dwordx8 s[48:55], s[80:81], 0x20
	s_load_dwordx4 s[56:59], s[80:81], 0x40
	s_load_dwordx4 s[76:79], s[80:81], 0x50
	s_load_dwordx2 s[98:99], s[80:81], 0x60
	s_load_dwordx2 s[100:101], s[80:81], 0x68
	s_load_dwordx2 s[26:27], s[80:81], 0x70
	s_load_dwordx2 s[28:29], s[80:81], 0x78
	v_mov_b32_e32 v200, s30
	v_mov_b32_e32 v201, s31
	v_mov_b32_e32 v202, s32
	v_mov_b32_e32 v203, s33
	v_lshlrev_b32_e32 v205, s67, v192
	v_cmp_lt_u32_e32 vcc, s61, v205
	v_sub_u32_e32 v206, s72, v205
	v_lshlrev_b32_e32 v206, 11, v206
	v_cndmask_b32_e32 v196, v202, v200, vcc
	v_cndmask_b32_e32 v197, v203, v201, vcc
	v_add_co_u32_e32 v196, vcc, v196, v206
	s_nop 1
	v_addc_co_u32_e32 v197, vcc, 0, v197, vcc
	v_cvt_f32_u32_e32 v182, v205
	v_add_u32_e32 v204, 64, v192
	v_lshlrev_b32_e32 v205, s67, v204
	v_cmp_lt_u32_e32 vcc, s61, v205
	v_sub_u32_e32 v206, s72, v205
	v_lshlrev_b32_e32 v206, 11, v206
	v_cndmask_b32_e32 v198, v202, v200, vcc
	v_cndmask_b32_e32 v199, v203, v201, vcc
	v_add_co_u32_e32 v198, vcc, v198, v206
	s_nop 1
	v_addc_co_u32_e32 v199, vcc, 0, v199, vcc
	v_cvt_f32_u32_e32 v183, v205
	global_load_dwordx4 v[0:3], v[196:197], off
	global_load_dwordx4 v[4:7], v[196:197], off offset:16
	global_load_dwordx4 v[8:11], v[196:197], off offset:32
	global_load_dwordx4 v[12:15], v[196:197], off offset:48
	global_load_dwordx4 v[16:19], v[196:197], off offset:64
	global_load_dwordx4 v[20:23], v[196:197], off offset:80
	global_load_dwordx4 v[24:27], v[196:197], off offset:96
	global_load_dwordx4 v[28:31], v[196:197], off offset:112
	global_load_dwordx4 v[32:35], v[196:197], off offset:128
	global_load_dwordx4 v[36:39], v[196:197], off offset:144
	global_load_dwordx4 v[40:43], v[196:197], off offset:160
	global_load_dwordx4 v[44:47], v[196:197], off offset:176
	global_load_dwordx4 v[48:51], v[196:197], off offset:192
	global_load_dwordx4 v[52:55], v[196:197], off offset:208
	global_load_dwordx4 v[56:59], v[196:197], off offset:224
	global_load_dwordx4 v[60:63], v[196:197], off offset:240
	global_load_dwordx4 v[64:67], v[198:199], off
	global_load_dwordx4 v[68:71], v[198:199], off offset:16
	global_load_dwordx4 v[72:75], v[198:199], off offset:32
	global_load_dwordx4 v[76:79], v[198:199], off offset:48
	global_load_dwordx4 v[80:83], v[198:199], off offset:64
	global_load_dwordx4 v[84:87], v[198:199], off offset:80
	global_load_dwordx4 v[88:91], v[198:199], off offset:96
	global_load_dwordx4 v[92:95], v[198:199], off offset:112
	global_load_dwordx4 v[96:99], v[198:199], off offset:128
	global_load_dwordx4 v[100:103], v[198:199], off offset:144
	global_load_dwordx4 v[104:107], v[198:199], off offset:160
	global_load_dwordx4 v[108:111], v[198:199], off offset:176
	global_load_dwordx4 v[112:115], v[198:199], off offset:192
	global_load_dwordx4 v[116:119], v[198:199], off offset:208
	global_load_dwordx4 v[120:123], v[198:199], off offset:224
; __device__ __forceinline__ void attn_sample_item(const Args& a, const bf16_t* qkvb, bf16_t* og, float* lse, int it, int lane) {
;     ...
;         const int j = lane + 64 * pass; const bool valid = j <= 128; const int jj = valid ? j : 128;
;         const int idx = W + t - jj * dil;
;         const float* kp = idx < W ? cache + (size_t)idx * 512 : kvs + (size_t)(idx - 8) * 512;
;         float dot = 0.f;
; #pragma unroll
;         for (int i = 0; i < 16; ++i) { const f32x4 k4 = *(const f32x4*)(kp + 4 * i); dot += (q[4 * i] * k4[0] + q[4 * i + 1] * k4[1]) + (q[4 * i + 2] * k4[2] + q[4 * i + 3] * k4[3]); }
;         sc[pass] = valid ? dot * 0.125f - slope * (float)(jj * dil) : -1e30f;
;     }
;     const float mx = wave_max(fmaxf(fmaxf(sc[0], sc[1]), sc[2]));
;     float p[3];
; #pragma unroll
;     for (int pass = 0; pass < 3; ++pass) p[pass] = sc[pass] > -1e29f ? __expf(sc[pass] - mx) : 0.f;
;     const float den = wave_sum(p[0] + p[1] + p[2]);
;     float o = 0.f;
; #pragma unroll 1
;     for (int j0 = 0; j0 < 128; j0 += 32) {
;         float v[32];
; #pragma unroll
;         for (int u = 0; u < 32; ++u) { const int idx = W + t - (j0 + u) * dil;
;             const float* vp = (idx < W ? cache + (size_t)idx * 512 : kvs + (size_t)(idx - 8) * 512) + 256; v[u] = vp[lane]; }
	global_load_dwordx4 v[124:127], v[198:199], off offset:240
	s_lshl_b32 s6, 0, s67
	s_sub_u32 s7, s72, s6
	s_lshl_b32 s7, s7, 11
	s_cmp_gt_u32 s6, s61
	s_cselect_b32 s36, s30, s32
	s_cselect_b32 s37, s31, s33
	s_add_u32 s36, s36, s7
	s_addc_u32 s37, s37, 0
	global_load_dword v220, v177, s[36:37] offset:1024
	s_lshl_b32 s6, 1, s67
	s_sub_u32 s7, s72, s6
	s_lshl_b32 s7, s7, 11
	s_cmp_gt_u32 s6, s61
	s_cselect_b32 s36, s30, s32
	s_cselect_b32 s37, s31, s33
	s_add_u32 s36, s36, s7
	s_addc_u32 s37, s37, 0
	global_load_dword v221, v177, s[36:37] offset:1024
	s_lshl_b32 s6, 2, s67
	s_sub_u32 s7, s72, s6
	s_lshl_b32 s7, s7, 11
	s_cmp_gt_u32 s6, s61
	s_cselect_b32 s36, s30, s32
	s_cselect_b32 s37, s31, s33
	s_add_u32 s36, s36, s7
	s_addc_u32 s37, s37, 0
	global_load_dword v222, v177, s[36:37] offset:1024
	s_lshl_b32 s6, 3, s67
	s_sub_u32 s7, s72, s6
	s_lshl_b32 s7, s7, 11
	s_cmp_gt_u32 s6, s61
	s_cselect_b32 s36, s30, s32
	s_cselect_b32 s37, s31, s33
	s_add_u32 s36, s36, s7
	s_addc_u32 s37, s37, 0
	global_load_dword v223, v177, s[36:37] offset:1024
	s_lshl_b32 s6, 4, s67
	s_sub_u32 s7, s72, s6
	s_lshl_b32 s7, s7, 11
	s_cmp_gt_u32 s6, s61
	s_cselect_b32 s36, s30, s32
	s_cselect_b32 s37, s31, s33
	s_add_u32 s36, s36, s7
	s_addc_u32 s37, s37, 0
	global_load_dword v224, v177, s[36:37] offset:1024
	s_lshl_b32 s6, 5, s67
	s_sub_u32 s7, s72, s6
	s_lshl_b32 s7, s7, 11
	s_cmp_gt_u32 s6, s61
	s_cselect_b32 s36, s30, s32
	s_cselect_b32 s37, s31, s33
	s_add_u32 s36, s36, s7
	s_addc_u32 s37, s37, 0
	global_load_dword v225, v177, s[36:37] offset:1024
	s_lshl_b32 s6, 6, s67
	s_sub_u32 s7, s72, s6
	s_lshl_b32 s7, s7, 11
	s_cmp_gt_u32 s6, s61
	s_cselect_b32 s36, s30, s32
	s_cselect_b32 s37, s31, s33
	s_add_u32 s36, s36, s7
	s_addc_u32 s37, s37, 0
	global_load_dword v226, v177, s[36:37] offset:1024
	s_lshl_b32 s6, 7, s67
	s_sub_u32 s7, s72, s6
	s_lshl_b32 s7, s7, 11
	s_cmp_gt_u32 s6, s61
	s_cselect_b32 s36, s30, s32
	s_cselect_b32 s37, s31, s33
	s_add_u32 s36, s36, s7
	s_addc_u32 s37, s37, 0
	global_load_dword v227, v177, s[36:37] offset:1024
	s_lshl_b32 s6, 8, s67
	s_sub_u32 s7, s72, s6
	s_lshl_b32 s7, s7, 11
	s_add_u32 s36, s30, s7
	s_addc_u32 s37, s31, 0
	s_lshl_b32 s7, 0x800, s67
	global_load_dword v228, v177, s[36:37] offset:1024
	s_sub_u32 s36, s36, s7
	s_subb_u32 s37, s37, 0
	global_load_dword v229, v177, s[36:37] offset:1024
	s_sub_u32 s36, s36, s7
	s_subb_u32 s37, s37, 0
	global_load_dword v230, v177, s[36:37] offset:1024
	s_sub_u32 s36, s36, s7
	s_subb_u32 s37, s37, 0
	global_load_dword v231, v177, s[36:37] offset:1024
	s_sub_u32 s36, s36, s7
	s_subb_u32 s37, s37, 0
	global_load_dword v232, v177, s[36:37] offset:1024
	s_sub_u32 s36, s36, s7
	s_subb_u32 s37, s37, 0
	global_load_dword v233, v177, s[36:37] offset:1024
	s_sub_u32 s36, s36, s7
	s_subb_u32 s37, s37, 0
	global_load_dword v234, v177, s[36:37] offset:1024
	s_sub_u32 s36, s36, s7
	s_subb_u32 s37, s37, 0
	global_load_dword v235, v177, s[36:37] offset:1024
	s_sub_u32 s36, s36, s7
	s_subb_u32 s37, s37, 0
	global_load_dword v236, v177, s[36:37] offset:1024
	s_sub_u32 s36, s36, s7
	s_subb_u32 s37, s37, 0
	global_load_dword v237, v177, s[36:37] offset:1024
	s_sub_u32 s36, s36, s7
	s_subb_u32 s37, s37, 0
	global_load_dword v238, v177, s[36:37] offset:1024
	s_sub_u32 s36, s36, s7
	s_subb_u32 s37, s37, 0
	global_load_dword v239, v177, s[36:37] offset:1024
	s_sub_u32 s36, s36, s7
	s_subb_u32 s37, s37, 0
	global_load_dword v240, v177, s[36:37] offset:1024
	s_sub_u32 s36, s36, s7
	s_subb_u32 s37, s37, 0
	global_load_dword v241, v177, s[36:37] offset:1024
	s_waitcnt lgkmcnt(0)
	s_waitcnt vmcnt(38)
	s_lshl_b32 s4, s40, 16
	s_and_b32 s6, s40, 0xffff0000
	v_mul_f32_e32 v185, s6, v1
	v_fmac_f32_e32 v185, s4, v0
	s_lshl_b32 s4, s41, 16
	s_and_b32 s6, s41, 0xffff0000
	v_mul_f32_e32 v186, s6, v3
	v_fmac_f32_e32 v186, s4, v2
	v_add_f32_e32 v185, v185, v186
	v_mov_b32_e32 v187, v185
	s_lshl_b32 s4, s42, 16
	s_and_b32 s6, s42, 0xffff0000
	v_mul_f32_e32 v185, s6, v5
	v_fmac_f32_e32 v185, s4, v4
	s_lshl_b32 s4, s43, 16
	s_and_b32 s6, s43, 0xffff0000
	v_mul_f32_e32 v186, s6, v7
	v_fmac_f32_e32 v186, s4, v6
	v_add_f32_e32 v185, v185, v186
	v_add_f32_e32 v187, v187, v185
	s_lshl_b32 s4, s44, 16
	s_and_b32 s6, s44, 0xffff0000
	v_mul_f32_e32 v185, s6, v9
	v_fmac_f32_e32 v185, s4, v8
	s_lshl_b32 s4, s45, 16
	s_and_b32 s6, s45, 0xffff0000
	v_mul_f32_e32 v186, s6, v11
	v_fmac_f32_e32 v186, s4, v10
	v_add_f32_e32 v185, v185, v186
	v_add_f32_e32 v187, v187, v185
	s_lshl_b32 s4, s46, 16
	s_and_b32 s6, s46, 0xffff0000
	v_mul_f32_e32 v185, s6, v13
	v_fmac_f32_e32 v185, s4, v12
	s_lshl_b32 s4, s47, 16
	s_and_b32 s6, s47, 0xffff0000
	v_mul_f32_e32 v186, s6, v15
	v_fmac_f32_e32 v186, s4, v14
	v_add_f32_e32 v185, v185, v186
	v_add_f32_e32 v187, v187, v185
	s_lshl_b32 s4, s48, 16
	s_and_b32 s6, s48, 0xffff0000
	v_mul_f32_e32 v185, s6, v17
	v_fmac_f32_e32 v185, s4, v16
	s_lshl_b32 s4, s49, 16
	s_and_b32 s6, s49, 0xffff0000
	v_mul_f32_e32 v186, s6, v19
	v_fmac_f32_e32 v186, s4, v18
	v_add_f32_e32 v185, v185, v186
	v_add_f32_e32 v187, v187, v185
	s_lshl_b32 s4, s50, 16
	s_and_b32 s6, s50, 0xffff0000
	v_mul_f32_e32 v185, s6, v21
	v_fmac_f32_e32 v185, s4, v20
	s_lshl_b32 s4, s51, 16
	s_and_b32 s6, s51, 0xffff0000
	v_mul_f32_e32 v186, s6, v23
	v_fmac_f32_e32 v186, s4, v22
	v_add_f32_e32 v185, v185, v186
	v_add_f32_e32 v187, v187, v185
	s_lshl_b32 s4, s52, 16
	s_and_b32 s6, s52, 0xffff0000
	v_mul_f32_e32 v185, s6, v25
	v_fmac_f32_e32 v185, s4, v24
	s_lshl_b32 s4, s53, 16
	s_and_b32 s6, s53, 0xffff0000
	v_mul_f32_e32 v186, s6, v27
	v_fmac_f32_e32 v186, s4, v26
	v_add_f32_e32 v185, v185, v186
	v_add_f32_e32 v187, v187, v185
	s_lshl_b32 s4, s54, 16
; __device__ __forceinline__ void attn_sample_item(const Args& a, const bf16_t* qkvb, bf16_t* og, float* lse, int it, int lane) {
;     ...
;         const int j = lane + 64 * pass; const bool valid = j <= 128; const int jj = valid ? j : 128;
;         const int idx = W + t - jj * dil;
;         const float* kp = idx < W ? cache + (size_t)idx * 512 : kvs + (size_t)(idx - 8) * 512;
;         float dot = 0.f;
; #pragma unroll
;         for (int i = 0; i < 16; ++i) { const f32x4 k4 = *(const f32x4*)(kp + 4 * i); dot += (q[4 * i] * k4[0] + q[4 * i + 1] * k4[1]) + (q[4 * i + 2] * k4[2] + q[4 * i + 3] * k4[3]); }
;         sc[pass] = valid ? dot * 0.125f - slope * (float)(jj * dil) : -1e30f;
	s_and_b32 s6, s54, 0xffff0000
	v_mul_f32_e32 v185, s6, v29
	v_fmac_f32_e32 v185, s4, v28
	s_lshl_b32 s4, s55, 16
	s_and_b32 s6, s55, 0xffff0000
	v_mul_f32_e32 v186, s6, v31
	v_fmac_f32_e32 v186, s4, v30
	v_add_f32_e32 v185, v185, v186
	v_add_f32_e32 v187, v187, v185
	s_lshl_b32 s4, s56, 16
	s_and_b32 s6, s56, 0xffff0000
	v_mul_f32_e32 v185, s6, v33
	v_fmac_f32_e32 v185, s4, v32
	s_lshl_b32 s4, s57, 16
	s_and_b32 s6, s57, 0xffff0000
	v_mul_f32_e32 v186, s6, v35
	v_fmac_f32_e32 v186, s4, v34
	v_add_f32_e32 v185, v185, v186
	v_add_f32_e32 v187, v187, v185
	s_lshl_b32 s4, s58, 16
	s_and_b32 s6, s58, 0xffff0000
	v_mul_f32_e32 v185, s6, v37
	v_fmac_f32_e32 v185, s4, v36
	s_lshl_b32 s4, s59, 16
	s_and_b32 s6, s59, 0xffff0000
	v_mul_f32_e32 v186, s6, v39
	v_fmac_f32_e32 v186, s4, v38
	v_add_f32_e32 v185, v185, v186
	v_add_f32_e32 v187, v187, v185
	s_lshl_b32 s4, s76, 16
	s_and_b32 s6, s76, 0xffff0000
	v_mul_f32_e32 v185, s6, v41
	v_fmac_f32_e32 v185, s4, v40
	s_lshl_b32 s4, s77, 16
	s_and_b32 s6, s77, 0xffff0000
	v_mul_f32_e32 v186, s6, v43
	v_fmac_f32_e32 v186, s4, v42
	v_add_f32_e32 v185, v185, v186
	v_add_f32_e32 v187, v187, v185
	s_lshl_b32 s4, s78, 16
	s_and_b32 s6, s78, 0xffff0000
	v_mul_f32_e32 v185, s6, v45
	v_fmac_f32_e32 v185, s4, v44
	s_lshl_b32 s4, s79, 16
	s_and_b32 s6, s79, 0xffff0000
	v_mul_f32_e32 v186, s6, v47
	v_fmac_f32_e32 v186, s4, v46
	v_add_f32_e32 v185, v185, v186
	v_add_f32_e32 v187, v187, v185
	s_lshl_b32 s4, s98, 16
	s_and_b32 s6, s98, 0xffff0000
	v_mul_f32_e32 v185, s6, v49
	v_fmac_f32_e32 v185, s4, v48
	s_lshl_b32 s4, s99, 16
	s_and_b32 s6, s99, 0xffff0000
	v_mul_f32_e32 v186, s6, v51
	v_fmac_f32_e32 v186, s4, v50
	v_add_f32_e32 v185, v185, v186
	v_add_f32_e32 v187, v187, v185
	s_lshl_b32 s4, s100, 16
	s_and_b32 s6, s100, 0xffff0000
	v_mul_f32_e32 v185, s6, v53
	v_fmac_f32_e32 v185, s4, v52
	s_lshl_b32 s4, s101, 16
	s_and_b32 s6, s101, 0xffff0000
	v_mul_f32_e32 v186, s6, v55
	v_fmac_f32_e32 v186, s4, v54
	v_add_f32_e32 v185, v185, v186
	v_add_f32_e32 v187, v187, v185
	s_lshl_b32 s4, s26, 16
	s_and_b32 s6, s26, 0xffff0000
	v_mul_f32_e32 v185, s6, v57
	v_fmac_f32_e32 v185, s4, v56
	s_lshl_b32 s4, s27, 16
	s_and_b32 s6, s27, 0xffff0000
	v_mul_f32_e32 v186, s6, v59
	v_fmac_f32_e32 v186, s4, v58
	v_add_f32_e32 v185, v185, v186
	v_add_f32_e32 v187, v187, v185
	s_lshl_b32 s4, s28, 16
	s_and_b32 s6, s28, 0xffff0000
	v_mul_f32_e32 v185, s6, v61
	v_fmac_f32_e32 v185, s4, v60
	s_lshl_b32 s4, s29, 16
	s_and_b32 s6, s29, 0xffff0000
	v_mul_f32_e32 v186, s6, v63
	v_fmac_f32_e32 v186, s4, v62
	v_add_f32_e32 v185, v185, v186
	v_add_f32_e32 v187, v187, v185
	v_mul_f32_e32 v187, 0x3e000000, v187
	v_mul_f32_e32 v182, s82, v182
	v_sub_f32_e32 v182, v187, v182
	s_lshl_b32 s6, s61, 11
	s_add_u32 s80, s30, s6
	s_addc_u32 s81, s31, 0
	global_load_dwordx4 v[0:3], v178, s[80:81]
	global_load_dwordx4 v[4:7], v178, s[80:81] offset:16
	global_load_dwordx4 v[8:11], v178, s[80:81] offset:32
	global_load_dwordx4 v[12:15], v178, s[80:81] offset:48
	global_load_dwordx4 v[16:19], v178, s[80:81] offset:64
	global_load_dwordx4 v[20:23], v178, s[80:81] offset:80
	global_load_dwordx4 v[24:27], v178, s[80:81] offset:96
	global_load_dwordx4 v[28:31], v178, s[80:81] offset:112
	global_load_dwordx4 v[32:35], v178, s[80:81] offset:128
	global_load_dwordx4 v[36:39], v178, s[80:81] offset:144
	global_load_dwordx4 v[40:43], v178, s[80:81] offset:160
	global_load_dwordx4 v[44:47], v178, s[80:81] offset:176
	global_load_dwordx4 v[48:51], v178, s[80:81] offset:192
	global_load_dwordx4 v[52:55], v178, s[80:81] offset:208
	global_load_dwordx4 v[56:59], v178, s[80:81] offset:224
	global_load_dwordx4 v[60:63], v178, s[80:81] offset:240
	s_waitcnt vmcnt(38)
	s_lshl_b32 s4, s40, 16
	s_and_b32 s6, s40, 0xffff0000
	v_mul_f32_e32 v185, s6, v65
	v_fmac_f32_e32 v185, s4, v64
	s_lshl_b32 s4, s41, 16
	s_and_b32 s6, s41, 0xffff0000
	v_mul_f32_e32 v186, s6, v67
	v_fmac_f32_e32 v186, s4, v66
	v_add_f32_e32 v185, v185, v186
	v_mov_b32_e32 v187, v185
	s_lshl_b32 s4, s42, 16
	s_and_b32 s6, s42, 0xffff0000
	v_mul_f32_e32 v185, s6, v69
	v_fmac_f32_e32 v185, s4, v68
	s_lshl_b32 s4, s43, 16
	s_and_b32 s6, s43, 0xffff0000
	v_mul_f32_e32 v186, s6, v71
	v_fmac_f32_e32 v186, s4, v70
	v_add_f32_e32 v185, v185, v186
	v_add_f32_e32 v187, v187, v185
	s_lshl_b32 s4, s44, 16
	s_and_b32 s6, s44, 0xffff0000
	v_mul_f32_e32 v185, s6, v73
	v_fmac_f32_e32 v185, s4, v72
	s_lshl_b32 s4, s45, 16
	s_and_b32 s6, s45, 0xffff0000
	v_mul_f32_e32 v186, s6, v75
	v_fmac_f32_e32 v186, s4, v74
	v_add_f32_e32 v185, v185, v186
	v_add_f32_e32 v187, v187, v185
	s_lshl_b32 s4, s46, 16
	s_and_b32 s6, s46, 0xffff0000
	v_mul_f32_e32 v185, s6, v77
	v_fmac_f32_e32 v185, s4, v76
	s_lshl_b32 s4, s47, 16
	s_and_b32 s6, s47, 0xffff0000
	v_mul_f32_e32 v186, s6, v79
	v_fmac_f32_e32 v186, s4, v78
	v_add_f32_e32 v185, v185, v186
	v_add_f32_e32 v187, v187, v185
	s_lshl_b32 s4, s48, 16
	s_and_b32 s6, s48, 0xffff0000
	v_mul_f32_e32 v185, s6, v81
	v_fmac_f32_e32 v185, s4, v80
	s_lshl_b32 s4, s49, 16
	s_and_b32 s6, s49, 0xffff0000
	v_mul_f32_e32 v186, s6, v83
	v_fmac_f32_e32 v186, s4, v82
	v_add_f32_e32 v185, v185, v186
	v_add_f32_e32 v187, v187, v185
	s_lshl_b32 s4, s50, 16
	s_and_b32 s6, s50, 0xffff0000
	v_mul_f32_e32 v185, s6, v85
	v_fmac_f32_e32 v185, s4, v84
	s_lshl_b32 s4, s51, 16
	s_and_b32 s6, s51, 0xffff0000
	v_mul_f32_e32 v186, s6, v87
	v_fmac_f32_e32 v186, s4, v86
	v_add_f32_e32 v185, v185, v186
	v_add_f32_e32 v187, v187, v185
	s_lshl_b32 s4, s52, 16
	s_and_b32 s6, s52, 0xffff0000
	v_mul_f32_e32 v185, s6, v89
	v_fmac_f32_e32 v185, s4, v88
	s_lshl_b32 s4, s53, 16
	s_and_b32 s6, s53, 0xffff0000
	v_mul_f32_e32 v186, s6, v91
; __device__ __forceinline__ void attn_sample_item(const Args& a, const bf16_t* qkvb, bf16_t* og, float* lse, int it, int lane) {
;     ...
;         for (int i = 0; i < 16; ++i) { const f32x4 k4 = *(const f32x4*)(kp + 4 * i); dot += (q[4 * i] * k4[0] + q[4 * i + 1] * k4[1]) + (q[4 * i + 2] * k4[2] + q[4 * i + 3] * k4[3]); }
;         sc[pass] = valid ? dot * 0.125f - slope * (float)(jj * dil) : -1e30f;
;     }
;     const float mx = wave_max(fmaxf(fmaxf(sc[0], sc[1]), sc[2]));
;     float p[3];
; #pragma unroll
;     for (int pass = 0; pass < 3; ++pass) p[pass] = sc[pass] > -1e29f ? __expf(sc[pass] - mx) : 0.f;
;     const float den = wave_sum(p[0] + p[1] + p[2]);
;     float o = 0.f;
; #pragma unroll 1
;     for (int j0 = 0; j0 < 128; j0 += 32) {
;         float v[32];
; #pragma unroll
;         for (int u = 0; u < 32; ++u) { const int idx = W + t - (j0 + u) * dil;
;             const float* vp = (idx < W ? cache + (size_t)idx * 512 : kvs + (size_t)(idx - 8) * 512) + 256; v[u] = vp[lane]; }
	v_fmac_f32_e32 v186, s4, v90
	v_add_f32_e32 v185, v185, v186
	v_add_f32_e32 v187, v187, v185
	s_lshl_b32 s4, s54, 16
	s_and_b32 s6, s54, 0xffff0000
	v_mul_f32_e32 v185, s6, v93
	v_fmac_f32_e32 v185, s4, v92
	s_lshl_b32 s4, s55, 16
	s_and_b32 s6, s55, 0xffff0000
	v_mul_f32_e32 v186, s6, v95
	v_fmac_f32_e32 v186, s4, v94
	v_add_f32_e32 v185, v185, v186
	v_add_f32_e32 v187, v187, v185
	s_lshl_b32 s4, s56, 16
	s_and_b32 s6, s56, 0xffff0000
	v_mul_f32_e32 v185, s6, v97
	v_fmac_f32_e32 v185, s4, v96
	s_lshl_b32 s4, s57, 16
	s_and_b32 s6, s57, 0xffff0000
	v_mul_f32_e32 v186, s6, v99
	v_fmac_f32_e32 v186, s4, v98
	v_add_f32_e32 v185, v185, v186
	v_add_f32_e32 v187, v187, v185
	s_lshl_b32 s4, s58, 16
	s_and_b32 s6, s58, 0xffff0000
	v_mul_f32_e32 v185, s6, v101
	v_fmac_f32_e32 v185, s4, v100
	s_lshl_b32 s4, s59, 16
	s_and_b32 s6, s59, 0xffff0000
	v_mul_f32_e32 v186, s6, v103
	v_fmac_f32_e32 v186, s4, v102
	v_add_f32_e32 v185, v185, v186
	v_add_f32_e32 v187, v187, v185
	s_lshl_b32 s4, s76, 16
	s_and_b32 s6, s76, 0xffff0000
	v_mul_f32_e32 v185, s6, v105
	v_fmac_f32_e32 v185, s4, v104
	s_lshl_b32 s4, s77, 16
	s_and_b32 s6, s77, 0xffff0000
	v_mul_f32_e32 v186, s6, v107
	v_fmac_f32_e32 v186, s4, v106
	v_add_f32_e32 v185, v185, v186
	v_add_f32_e32 v187, v187, v185
	s_lshl_b32 s4, s78, 16
	s_and_b32 s6, s78, 0xffff0000
	v_mul_f32_e32 v185, s6, v109
	v_fmac_f32_e32 v185, s4, v108
	s_lshl_b32 s4, s79, 16
	s_and_b32 s6, s79, 0xffff0000
	v_mul_f32_e32 v186, s6, v111
	v_fmac_f32_e32 v186, s4, v110
	v_add_f32_e32 v185, v185, v186
	v_add_f32_e32 v187, v187, v185
	s_lshl_b32 s4, s98, 16
	s_and_b32 s6, s98, 0xffff0000
	v_mul_f32_e32 v185, s6, v113
	v_fmac_f32_e32 v185, s4, v112
	s_lshl_b32 s4, s99, 16
	s_and_b32 s6, s99, 0xffff0000
	v_mul_f32_e32 v186, s6, v115
	v_fmac_f32_e32 v186, s4, v114
	v_add_f32_e32 v185, v185, v186
	v_add_f32_e32 v187, v187, v185
	s_lshl_b32 s4, s100, 16
	s_and_b32 s6, s100, 0xffff0000
	v_mul_f32_e32 v185, s6, v117
	v_fmac_f32_e32 v185, s4, v116
	s_lshl_b32 s4, s101, 16
	s_and_b32 s6, s101, 0xffff0000
	v_mul_f32_e32 v186, s6, v119
	v_fmac_f32_e32 v186, s4, v118
	v_add_f32_e32 v185, v185, v186
	v_add_f32_e32 v187, v187, v185
	s_lshl_b32 s4, s26, 16
	s_and_b32 s6, s26, 0xffff0000
	v_mul_f32_e32 v185, s6, v121
	v_fmac_f32_e32 v185, s4, v120
	s_lshl_b32 s4, s27, 16
	s_and_b32 s6, s27, 0xffff0000
	v_mul_f32_e32 v186, s6, v123
	v_fmac_f32_e32 v186, s4, v122
	v_add_f32_e32 v185, v185, v186
	v_add_f32_e32 v187, v187, v185
	s_lshl_b32 s4, s28, 16
	s_and_b32 s6, s28, 0xffff0000
	v_mul_f32_e32 v185, s6, v125
	v_fmac_f32_e32 v185, s4, v124
	s_lshl_b32 s4, s29, 16
	s_and_b32 s6, s29, 0xffff0000
	v_mul_f32_e32 v186, s6, v127
	v_fmac_f32_e32 v186, s4, v126
	v_add_f32_e32 v185, v185, v186
	v_add_f32_e32 v187, v187, v185
	v_mul_f32_e32 v187, 0x3e000000, v187
	v_mul_f32_e32 v183, s82, v183
	v_sub_f32_e32 v183, v187, v183
	s_sub_u32 s36, s36, s7
	s_subb_u32 s37, s37, 0
	global_load_dword v64, v177, s[36:37] offset:1024
	s_sub_u32 s36, s36, s7
	s_subb_u32 s37, s37, 0
	global_load_dword v65, v177, s[36:37] offset:1024
	s_sub_u32 s36, s36, s7
	s_subb_u32 s37, s37, 0
	global_load_dword v66, v177, s[36:37] offset:1024
	s_sub_u32 s36, s36, s7
	s_subb_u32 s37, s37, 0
	global_load_dword v67, v177, s[36:37] offset:1024
	s_sub_u32 s36, s36, s7
	s_subb_u32 s37, s37, 0
	global_load_dword v68, v177, s[36:37] offset:1024
	s_sub_u32 s36, s36, s7
	s_subb_u32 s37, s37, 0
	global_load_dword v69, v177, s[36:37] offset:1024
	s_sub_u32 s36, s36, s7
	s_subb_u32 s37, s37, 0
	global_load_dword v70, v177, s[36:37] offset:1024
	s_sub_u32 s36, s36, s7
	s_subb_u32 s37, s37, 0
	global_load_dword v71, v177, s[36:37] offset:1024
	s_sub_u32 s36, s36, s7
	s_subb_u32 s37, s37, 0
	global_load_dword v72, v177, s[36:37] offset:1024
	s_sub_u32 s36, s36, s7
	s_subb_u32 s37, s37, 0
	global_load_dword v73, v177, s[36:37] offset:1024
	s_sub_u32 s36, s36, s7
	s_subb_u32 s37, s37, 0
	global_load_dword v74, v177, s[36:37] offset:1024
	s_sub_u32 s36, s36, s7
	s_subb_u32 s37, s37, 0
	global_load_dword v75, v177, s[36:37] offset:1024
	s_sub_u32 s36, s36, s7
	s_subb_u32 s37, s37, 0
	global_load_dword v76, v177, s[36:37] offset:1024
	s_sub_u32 s36, s36, s7
	s_subb_u32 s37, s37, 0
	global_load_dword v77, v177, s[36:37] offset:1024
	s_sub_u32 s36, s36, s7
	s_subb_u32 s37, s37, 0
	global_load_dword v78, v177, s[36:37] offset:1024
	s_sub_u32 s36, s36, s7
	s_subb_u32 s37, s37, 0
	global_load_dword v79, v177, s[36:37] offset:1024
	s_sub_u32 s36, s36, s7
	s_subb_u32 s37, s37, 0
	global_load_dword v80, v177, s[36:37] offset:1024
	s_sub_u32 s36, s36, s7
	s_subb_u32 s37, s37, 0
	global_load_dword v81, v177, s[36:37] offset:1024
	s_sub_u32 s36, s36, s7
	s_subb_u32 s37, s37, 0
	global_load_dword v82, v177, s[36:37] offset:1024
	s_sub_u32 s36, s36, s7
	s_subb_u32 s37, s37, 0
	global_load_dword v83, v177, s[36:37] offset:1024
	s_sub_u32 s36, s36, s7
	s_subb_u32 s37, s37, 0
	global_load_dword v84, v177, s[36:37] offset:1024
	s_sub_u32 s36, s36, s7
	s_subb_u32 s37, s37, 0
	global_load_dword v85, v177, s[36:37] offset:1024
	s_waitcnt vmcnt(22)
; __device__ __forceinline__ void attn_sample_item(const Args& a, const bf16_t* qkvb, bf16_t* og, float* lse, int it, int lane) {
;     ...
;         const int j = lane + 64 * pass; const bool valid = j <= 128; const int jj = valid ? j : 128;
;         const int idx = W + t - jj * dil;
;         const float* kp = idx < W ? cache + (size_t)idx * 512 : kvs + (size_t)(idx - 8) * 512;
;         float dot = 0.f;
; #pragma unroll
;         for (int i = 0; i < 16; ++i) { const f32x4 k4 = *(const f32x4*)(kp + 4 * i); dot += (q[4 * i] * k4[0] + q[4 * i + 1] * k4[1]) + (q[4 * i + 2] * k4[2] + q[4 * i + 3] * k4[3]); }
;         sc[pass] = valid ? dot * 0.125f - slope * (float)(jj * dil) : -1e30f;
;     }
;     const float mx = wave_max(fmaxf(fmaxf(sc[0], sc[1]), sc[2]));
;     float p[3];
; #pragma unroll
;     for (int pass = 0; pass < 3; ++pass) p[pass] = sc[pass] > -1e29f ? __expf(sc[pass] - mx) : 0.f;
;     const float den = wave_sum(p[0] + p[1] + p[2]);
;     float o = 0.f;
; #pragma unroll 1
;     for (int j0 = 0; j0 < 128; j0 += 32) {
;         float v[32];
; #pragma unroll
;         for (int u = 0; u < 32; ++u) { const int idx = W + t - (j0 + u) * dil;
;             const float* vp = (idx < W ? cache + (size_t)idx * 512 : kvs + (size_t)(idx - 8) * 512) + 256; v[u] = vp[lane]; }
	s_lshl_b32 s4, s40, 16
	s_and_b32 s6, s40, 0xffff0000
	v_mul_f32_e32 v185, s6, v1
	v_fmac_f32_e32 v185, s4, v0
	s_lshl_b32 s4, s41, 16
	s_and_b32 s6, s41, 0xffff0000
	v_mul_f32_e32 v186, s6, v3
	v_fmac_f32_e32 v186, s4, v2
	v_add_f32_e32 v185, v185, v186
	v_mov_b32_e32 v187, v185
	s_lshl_b32 s4, s42, 16
	s_and_b32 s6, s42, 0xffff0000
	v_mul_f32_e32 v185, s6, v5
	v_fmac_f32_e32 v185, s4, v4
	s_lshl_b32 s4, s43, 16
	s_and_b32 s6, s43, 0xffff0000
	v_mul_f32_e32 v186, s6, v7
	v_fmac_f32_e32 v186, s4, v6
	v_add_f32_e32 v185, v185, v186
	v_add_f32_e32 v187, v187, v185
	s_lshl_b32 s4, s44, 16
	s_and_b32 s6, s44, 0xffff0000
	v_mul_f32_e32 v185, s6, v9
	v_fmac_f32_e32 v185, s4, v8
	s_lshl_b32 s4, s45, 16
	s_and_b32 s6, s45, 0xffff0000
	v_mul_f32_e32 v186, s6, v11
	v_fmac_f32_e32 v186, s4, v10
	v_add_f32_e32 v185, v185, v186
	v_add_f32_e32 v187, v187, v185
	s_lshl_b32 s4, s46, 16
	s_and_b32 s6, s46, 0xffff0000
	v_mul_f32_e32 v185, s6, v13
	v_fmac_f32_e32 v185, s4, v12
	s_lshl_b32 s4, s47, 16
	s_and_b32 s6, s47, 0xffff0000
	v_mul_f32_e32 v186, s6, v15
	v_fmac_f32_e32 v186, s4, v14
	v_add_f32_e32 v185, v185, v186
	v_add_f32_e32 v187, v187, v185
	s_lshl_b32 s4, s48, 16
	s_and_b32 s6, s48, 0xffff0000
	v_mul_f32_e32 v185, s6, v17
	v_fmac_f32_e32 v185, s4, v16
	s_lshl_b32 s4, s49, 16
	s_and_b32 s6, s49, 0xffff0000
	v_mul_f32_e32 v186, s6, v19
	v_fmac_f32_e32 v186, s4, v18
	v_add_f32_e32 v185, v185, v186
	v_add_f32_e32 v187, v187, v185
	s_lshl_b32 s4, s50, 16
	s_and_b32 s6, s50, 0xffff0000
	v_mul_f32_e32 v185, s6, v21
	v_fmac_f32_e32 v185, s4, v20
	s_lshl_b32 s4, s51, 16
	s_and_b32 s6, s51, 0xffff0000
	v_mul_f32_e32 v186, s6, v23
	v_fmac_f32_e32 v186, s4, v22
	v_add_f32_e32 v185, v185, v186
	v_add_f32_e32 v187, v187, v185
	s_lshl_b32 s4, s52, 16
	s_and_b32 s6, s52, 0xffff0000
	v_mul_f32_e32 v185, s6, v25
	v_fmac_f32_e32 v185, s4, v24
	s_lshl_b32 s4, s53, 16
	s_and_b32 s6, s53, 0xffff0000
	v_mul_f32_e32 v186, s6, v27
	v_fmac_f32_e32 v186, s4, v26
	v_add_f32_e32 v185, v185, v186
	v_add_f32_e32 v187, v187, v185
	s_lshl_b32 s4, s54, 16
	s_and_b32 s6, s54, 0xffff0000
	v_mul_f32_e32 v185, s6, v29
	v_fmac_f32_e32 v185, s4, v28
	s_lshl_b32 s4, s55, 16
	s_and_b32 s6, s55, 0xffff0000
	v_mul_f32_e32 v186, s6, v31
	v_fmac_f32_e32 v186, s4, v30
	v_add_f32_e32 v185, v185, v186
	v_add_f32_e32 v187, v187, v185
	s_lshl_b32 s4, s56, 16
	s_and_b32 s6, s56, 0xffff0000
	v_mul_f32_e32 v185, s6, v33
	v_fmac_f32_e32 v185, s4, v32
	s_lshl_b32 s4, s57, 16
	s_and_b32 s6, s57, 0xffff0000
	v_mul_f32_e32 v186, s6, v35
	v_fmac_f32_e32 v186, s4, v34
	v_add_f32_e32 v185, v185, v186
	v_add_f32_e32 v187, v187, v185
	s_lshl_b32 s4, s58, 16
	s_and_b32 s6, s58, 0xffff0000
	v_mul_f32_e32 v185, s6, v37
	v_fmac_f32_e32 v185, s4, v36
	s_lshl_b32 s4, s59, 16
	s_and_b32 s6, s59, 0xffff0000
	v_mul_f32_e32 v186, s6, v39
	v_fmac_f32_e32 v186, s4, v38
	v_add_f32_e32 v185, v185, v186
	v_add_f32_e32 v187, v187, v185
	s_lshl_b32 s4, s76, 16
	s_and_b32 s6, s76, 0xffff0000
	v_mul_f32_e32 v185, s6, v41
	v_fmac_f32_e32 v185, s4, v40
	s_lshl_b32 s4, s77, 16
	s_and_b32 s6, s77, 0xffff0000
	v_mul_f32_e32 v186, s6, v43
	v_fmac_f32_e32 v186, s4, v42
	v_add_f32_e32 v185, v185, v186
	v_add_f32_e32 v187, v187, v185
	s_lshl_b32 s4, s78, 16
	s_and_b32 s6, s78, 0xffff0000
	v_mul_f32_e32 v185, s6, v45
	v_fmac_f32_e32 v185, s4, v44
	s_lshl_b32 s4, s79, 16
	s_and_b32 s6, s79, 0xffff0000
	v_mul_f32_e32 v186, s6, v47
	v_fmac_f32_e32 v186, s4, v46
	v_add_f32_e32 v185, v185, v186
	v_add_f32_e32 v187, v187, v185
	s_lshl_b32 s4, s98, 16
	s_and_b32 s6, s98, 0xffff0000
	v_mul_f32_e32 v185, s6, v49
	v_fmac_f32_e32 v185, s4, v48
	s_lshl_b32 s4, s99, 16
	s_and_b32 s6, s99, 0xffff0000
	v_mul_f32_e32 v186, s6, v51
	v_fmac_f32_e32 v186, s4, v50
	v_add_f32_e32 v185, v185, v186
	v_add_f32_e32 v187, v187, v185
	s_lshl_b32 s4, s100, 16
	s_and_b32 s6, s100, 0xffff0000
	v_mul_f32_e32 v185, s6, v53
	v_fmac_f32_e32 v185, s4, v52
	s_lshl_b32 s4, s101, 16
	s_and_b32 s6, s101, 0xffff0000
	v_mul_f32_e32 v186, s6, v55
	v_fmac_f32_e32 v186, s4, v54
	v_add_f32_e32 v185, v185, v186
	v_add_f32_e32 v187, v187, v185
	s_lshl_b32 s4, s26, 16
	s_and_b32 s6, s26, 0xffff0000
	v_mul_f32_e32 v185, s6, v57
	v_fmac_f32_e32 v185, s4, v56
	s_lshl_b32 s4, s27, 16
	s_and_b32 s6, s27, 0xffff0000
	v_mul_f32_e32 v186, s6, v59
	v_fmac_f32_e32 v186, s4, v58
	v_add_f32_e32 v185, v185, v186
	v_add_f32_e32 v187, v187, v185
	s_lshl_b32 s4, s28, 16
	s_and_b32 s6, s28, 0xffff0000
	v_mul_f32_e32 v185, s6, v61
	v_fmac_f32_e32 v185, s4, v60
	s_lshl_b32 s4, s29, 16
	s_and_b32 s6, s29, 0xffff0000
	v_mul_f32_e32 v186, s6, v63
	v_fmac_f32_e32 v186, s4, v62
	v_add_f32_e32 v185, v185, v186
	v_add_f32_e32 v187, v187, v185
	v_mul_f32_e32 v187, 0x3e000000, v187
	s_lshl_b32 s6, 0x80, s67
	v_cvt_f32_u32_e32 v184, s6
	v_mul_f32_e32 v184, s82, v184
	v_sub_f32_e32 v184, v187, v184
	v_mov_b32_e32 v191, 0xf149f2ca
	v_cmp_eq_u32_e32 vcc, 0, v192
	s_nop 1
	v_cndmask_b32_e32 v184, v191, v184, vcc
	s_sub_u32 s36, s36, s7
	s_subb_u32 s37, s37, 0
	global_load_dword v86, v177, s[36:37] offset:1024
	s_sub_u32 s36, s36, s7
	s_subb_u32 s37, s37, 0
	global_load_dword v87, v177, s[36:37] offset:1024
	s_sub_u32 s36, s36, s7
	s_subb_u32 s37, s37, 0
	global_load_dword v88, v177, s[36:37] offset:1024
	s_sub_u32 s36, s36, s7
	s_subb_u32 s37, s37, 0
	global_load_dword v89, v177, s[36:37] offset:1024
	s_sub_u32 s36, s36, s7
	s_subb_u32 s37, s37, 0
	global_load_dword v90, v177, s[36:37] offset:1024
	s_sub_u32 s36, s36, s7
	s_subb_u32 s37, s37, 0
	global_load_dword v91, v177, s[36:37] offset:1024
	s_sub_u32 s36, s36, s7
	s_subb_u32 s37, s37, 0
	global_load_dword v92, v177, s[36:37] offset:1024
	s_sub_u32 s36, s36, s7
; __device__ __forceinline__ void attn_sample_item(const Args& a, const bf16_t* qkvb, bf16_t* og, float* lse, int it, int lane) {
;     ...
;     const float mx = wave_max(fmaxf(fmaxf(sc[0], sc[1]), sc[2]));
;     float p[3];
; #pragma unroll
;     for (int pass = 0; pass < 3; ++pass) p[pass] = sc[pass] > -1e29f ? __expf(sc[pass] - mx) : 0.f;
;     const float den = wave_sum(p[0] + p[1] + p[2]);
;     float o = 0.f;
; #pragma unroll 1
;     for (int j0 = 0; j0 < 128; j0 += 32) {
;         float v[32];
; #pragma unroll
;         for (int u = 0; u < 32; ++u) { const int idx = W + t - (j0 + u) * dil;
;             const float* vp = (idx < W ? cache + (size_t)idx * 512 : kvs + (size_t)(idx - 8) * 512) + 256; v[u] = vp[lane]; }
;         const float psrc = j0 < 64 ? p[0] : p[1];
; #pragma unroll
;         for (int u = 0; u < 32; ++u) o += __shfl(psrc, (j0 & 63) + u) * v[u];
	s_subb_u32 s37, s37, 0
	global_load_dword v93, v177, s[36:37] offset:1024
	s_sub_u32 s36, s36, s7
	s_subb_u32 s37, s37, 0
	global_load_dword v94, v177, s[36:37] offset:1024
	s_sub_u32 s36, s36, s7
	s_subb_u32 s37, s37, 0
	global_load_dword v95, v177, s[36:37] offset:1024
	s_sub_u32 s36, s36, s7
	s_subb_u32 s37, s37, 0
	global_load_dword v96, v177, s[36:37] offset:1024
	s_sub_u32 s36, s36, s7
	s_subb_u32 s37, s37, 0
	global_load_dword v97, v177, s[36:37] offset:1024
	s_sub_u32 s36, s36, s7
	s_subb_u32 s37, s37, 0
	global_load_dword v98, v177, s[36:37] offset:1024
	s_sub_u32 s36, s36, s7
	s_subb_u32 s37, s37, 0
	global_load_dword v99, v177, s[36:37] offset:1024
	s_sub_u32 s36, s36, s7
	s_subb_u32 s37, s37, 0
	global_load_dword v100, v177, s[36:37] offset:1024
	s_sub_u32 s36, s36, s7
	s_subb_u32 s37, s37, 0
	global_load_dword v101, v177, s[36:37] offset:1024
	s_sub_u32 s36, s36, s7
	s_subb_u32 s37, s37, 0
	global_load_dword v102, v177, s[36:37] offset:1024
	s_sub_u32 s36, s36, s7
	s_subb_u32 s37, s37, 0
	global_load_dword v103, v177, s[36:37] offset:1024
	s_sub_u32 s36, s36, s7
	s_subb_u32 s37, s37, 0
	global_load_dword v104, v177, s[36:37] offset:1024
	s_sub_u32 s36, s36, s7
	s_subb_u32 s37, s37, 0
	global_load_dword v105, v177, s[36:37] offset:1024
	s_sub_u32 s36, s36, s7
	s_subb_u32 s37, s37, 0
	global_load_dword v106, v177, s[36:37] offset:1024
	s_sub_u32 s36, s36, s7
	s_subb_u32 s37, s37, 0
	global_load_dword v107, v177, s[36:37] offset:1024
	s_sub_u32 s36, s36, s7
	s_subb_u32 s37, s37, 0
	global_load_dword v108, v177, s[36:37] offset:1024
	s_sub_u32 s36, s36, s7
	s_subb_u32 s37, s37, 0
	global_load_dword v109, v177, s[36:37] offset:1024
	s_sub_u32 s36, s36, s7
	s_subb_u32 s37, s37, 0
	global_load_dword v110, v177, s[36:37] offset:1024
	s_sub_u32 s36, s36, s7
	s_subb_u32 s37, s37, 0
	global_load_dword v111, v177, s[36:37] offset:1024
	s_sub_u32 s36, s36, s7
	s_subb_u32 s37, s37, 0
	global_load_dword v112, v177, s[36:37] offset:1024
	s_sub_u32 s36, s36, s7
	s_subb_u32 s37, s37, 0
	global_load_dword v113, v177, s[36:37] offset:1024
	s_sub_u32 s36, s36, s7
	s_subb_u32 s37, s37, 0
	global_load_dword v114, v177, s[36:37] offset:1024
	s_sub_u32 s36, s36, s7
	s_subb_u32 s37, s37, 0
	global_load_dword v115, v177, s[36:37] offset:1024
	s_sub_u32 s36, s36, s7
	s_subb_u32 s37, s37, 0
	global_load_dword v116, v177, s[36:37] offset:1024
	s_sub_u32 s36, s36, s7
	s_subb_u32 s37, s37, 0
	global_load_dword v117, v177, s[36:37] offset:1024
	s_sub_u32 s36, s36, s7
	s_subb_u32 s37, s37, 0
	global_load_dword v118, v177, s[36:37] offset:1024
	s_sub_u32 s36, s36, s7
	s_subb_u32 s37, s37, 0
	global_load_dword v119, v177, s[36:37] offset:1024
	s_sub_u32 s36, s36, s7
	s_subb_u32 s37, s37, 0
	global_load_dword v120, v177, s[36:37] offset:1024
	s_sub_u32 s36, s36, s7
	s_subb_u32 s37, s37, 0
	global_load_dword v121, v177, s[36:37] offset:1024
	s_sub_u32 s36, s36, s7
	s_subb_u32 s37, s37, 0
	global_load_dword v122, v177, s[36:37] offset:1024
	s_sub_u32 s36, s36, s7
	s_subb_u32 s37, s37, 0
	global_load_dword v123, v177, s[36:37] offset:1024
	v_max3_f32 v188, v182, v183, v184
	ds_bpermute_b32 v191, v171, v188
	s_waitcnt lgkmcnt(0)
	v_max_f32_e32 v188, v188, v191
	ds_bpermute_b32 v191, v172, v188
	s_waitcnt lgkmcnt(0)
	v_max_f32_e32 v188, v188, v191
	ds_bpermute_b32 v191, v173, v188
	s_waitcnt lgkmcnt(0)
	v_max_f32_e32 v188, v188, v191
	ds_bpermute_b32 v191, v174, v188
	s_waitcnt lgkmcnt(0)
	v_max_f32_e32 v188, v188, v191
	ds_bpermute_b32 v191, v175, v188
	s_waitcnt lgkmcnt(0)
	v_max_f32_e32 v188, v188, v191
	ds_bpermute_b32 v191, v176, v188
	s_waitcnt lgkmcnt(0)
	v_max_f32_e32 v188, v188, v191
	v_sub_f32_e32 v179, v182, v188
	v_mul_f32_e32 v179, 0x3fb8aa3b, v179
	v_exp_f32_e32 v179, v179
	v_sub_f32_e32 v180, v183, v188
	v_mul_f32_e32 v180, 0x3fb8aa3b, v180
	v_exp_f32_e32 v180, v180
	v_sub_f32_e32 v181, v184, v188
	v_mul_f32_e32 v181, 0x3fb8aa3b, v181
	v_exp_f32_e32 v181, v181
	s_nop 0
	v_add_f32_e32 v189, v179, v180
	v_add_f32_e32 v189, v189, v181
	ds_bpermute_b32 v191, v171, v189
	s_waitcnt lgkmcnt(0)
	v_add_f32_e32 v189, v189, v191
	ds_bpermute_b32 v191, v172, v189
	s_waitcnt lgkmcnt(0)
	v_add_f32_e32 v189, v189, v191
	ds_bpermute_b32 v191, v173, v189
	s_waitcnt lgkmcnt(0)
	v_add_f32_e32 v189, v189, v191
	ds_bpermute_b32 v191, v174, v189
	s_waitcnt lgkmcnt(0)
	v_add_f32_e32 v189, v189, v191
	ds_bpermute_b32 v191, v175, v189
	s_waitcnt lgkmcnt(0)
	v_add_f32_e32 v189, v189, v191
	ds_bpermute_b32 v191, v176, v189
	s_waitcnt lgkmcnt(0)
	v_add_f32_e32 v189, v189, v191
	v_mov_b32_e32 v190, 0
	v_readlane_b32 s40, v179, 0
	v_readlane_b32 s41, v179, 1
	v_readlane_b32 s42, v179, 2
	v_readlane_b32 s43, v179, 3
	v_readlane_b32 s44, v179, 4
	v_readlane_b32 s45, v179, 5
	v_readlane_b32 s46, v179, 6
	v_readlane_b32 s47, v179, 7
	v_fmac_f32_e32 v190, s40, v220
	v_fmac_f32_e32 v190, s41, v221
	v_fmac_f32_e32 v190, s42, v222
	v_fmac_f32_e32 v190, s43, v223
	v_fmac_f32_e32 v190, s44, v224
	v_fmac_f32_e32 v190, s45, v225
	v_fmac_f32_e32 v190, s46, v226
	v_fmac_f32_e32 v190, s47, v227
	v_readlane_b32 s40, v179, 8
	v_readlane_b32 s41, v179, 9
	v_readlane_b32 s42, v179, 10
	v_readlane_b32 s43, v179, 11
	v_readlane_b32 s44, v179, 12
	v_readlane_b32 s45, v179, 13
	v_readlane_b32 s46, v179, 14
	v_readlane_b32 s47, v179, 15
	v_fmac_f32_e32 v190, s40, v228
	v_fmac_f32_e32 v190, s41, v229
	v_fmac_f32_e32 v190, s42, v230
	v_fmac_f32_e32 v190, s43, v231
	v_fmac_f32_e32 v190, s44, v232
	v_fmac_f32_e32 v190, s45, v233
	v_fmac_f32_e32 v190, s46, v234
	v_fmac_f32_e32 v190, s47, v235
	s_waitcnt vmcnt(58)
; __device__ __forceinline__ void attn_sample_item(const Args& a, const bf16_t* qkvb, bf16_t* og, float* lse, int it, int lane) {
;     ...
;     for (int j0 = 0; j0 < 128; j0 += 32) {
;         float v[32];
; #pragma unroll
;         for (int u = 0; u < 32; ++u) { const int idx = W + t - (j0 + u) * dil;
;             const float* vp = (idx < W ? cache + (size_t)idx * 512 : kvs + (size_t)(idx - 8) * 512) + 256; v[u] = vp[lane]; }
;         const float psrc = j0 < 64 ? p[0] : p[1];
; #pragma unroll
;         for (int u = 0; u < 32; ++u) o += __shfl(psrc, (j0 & 63) + u) * v[u];
	v_readlane_b32 s40, v179, 16
	v_readlane_b32 s41, v179, 17
	v_readlane_b32 s42, v179, 18
	v_readlane_b32 s43, v179, 19
	v_readlane_b32 s44, v179, 20
	v_readlane_b32 s45, v179, 21
	v_readlane_b32 s46, v179, 22
	v_readlane_b32 s47, v179, 23
	v_fmac_f32_e32 v190, s40, v236
	v_fmac_f32_e32 v190, s41, v237
	v_fmac_f32_e32 v190, s42, v238
	v_fmac_f32_e32 v190, s43, v239
	v_fmac_f32_e32 v190, s44, v240
	v_fmac_f32_e32 v190, s45, v241
	v_fmac_f32_e32 v190, s46, v64
	v_fmac_f32_e32 v190, s47, v65
	s_sub_u32 s36, s36, s7
	s_subb_u32 s37, s37, 0
	global_load_dword v124, v177, s[36:37] offset:1024
	s_sub_u32 s36, s36, s7
	s_subb_u32 s37, s37, 0
	global_load_dword v125, v177, s[36:37] offset:1024
	s_waitcnt vmcnt(52)
	v_readlane_b32 s40, v179, 24
	v_readlane_b32 s41, v179, 25
	v_readlane_b32 s42, v179, 26
	v_readlane_b32 s43, v179, 27
	v_readlane_b32 s44, v179, 28
	v_readlane_b32 s45, v179, 29
	v_readlane_b32 s46, v179, 30
	v_readlane_b32 s47, v179, 31
	v_fmac_f32_e32 v190, s40, v66
	v_fmac_f32_e32 v190, s41, v67
	v_fmac_f32_e32 v190, s42, v68
	v_fmac_f32_e32 v190, s43, v69
	v_fmac_f32_e32 v190, s44, v70
	v_fmac_f32_e32 v190, s45, v71
	v_fmac_f32_e32 v190, s46, v72
	v_fmac_f32_e32 v190, s47, v73
	s_sub_u32 s36, s36, s7
	s_subb_u32 s37, s37, 0
	global_load_dword v126, v177, s[36:37] offset:1024
	s_sub_u32 s36, s36, s7
	s_subb_u32 s37, s37, 0
	global_load_dword v127, v177, s[36:37] offset:1024
	s_sub_u32 s36, s36, s7
	s_subb_u32 s37, s37, 0
	global_load_dword v0, v177, s[36:37] offset:1024
	s_sub_u32 s36, s36, s7
	s_subb_u32 s37, s37, 0
	global_load_dword v1, v177, s[36:37] offset:1024
	s_sub_u32 s36, s36, s7
	s_subb_u32 s37, s37, 0
	global_load_dword v2, v177, s[36:37] offset:1024
	s_sub_u32 s36, s36, s7
	s_subb_u32 s37, s37, 0
	global_load_dword v3, v177, s[36:37] offset:1024
	s_sub_u32 s36, s36, s7
	s_subb_u32 s37, s37, 0
	global_load_dword v4, v177, s[36:37] offset:1024
	s_sub_u32 s36, s36, s7
	s_subb_u32 s37, s37, 0
	global_load_dword v5, v177, s[36:37] offset:1024
	s_waitcnt vmcnt(52)
	v_readlane_b32 s40, v179, 32
	v_readlane_b32 s41, v179, 33
	v_readlane_b32 s42, v179, 34
	v_readlane_b32 s43, v179, 35
	v_readlane_b32 s44, v179, 36
	v_readlane_b32 s45, v179, 37
	v_readlane_b32 s46, v179, 38
	v_readlane_b32 s47, v179, 39
	v_fmac_f32_e32 v190, s40, v74
	v_fmac_f32_e32 v190, s41, v75
	v_fmac_f32_e32 v190, s42, v76
	v_fmac_f32_e32 v190, s43, v77
	v_fmac_f32_e32 v190, s44, v78
	v_fmac_f32_e32 v190, s45, v79
	v_fmac_f32_e32 v190, s46, v80
	v_fmac_f32_e32 v190, s47, v81
	s_sub_u32 s36, s36, s7
	s_subb_u32 s37, s37, 0
	global_load_dword v6, v177, s[36:37] offset:1024
	s_sub_u32 s36, s36, s7
	s_subb_u32 s37, s37, 0
	global_load_dword v7, v177, s[36:37] offset:1024
	s_sub_u32 s36, s36, s7
	s_subb_u32 s37, s37, 0
	global_load_dword v8, v177, s[36:37] offset:1024
	s_sub_u32 s36, s36, s7
	s_subb_u32 s37, s37, 0
	global_load_dword v9, v177, s[36:37] offset:1024
	s_sub_u32 s36, s36, s7
	s_subb_u32 s37, s37, 0
	global_load_dword v10, v177, s[36:37] offset:1024
	s_sub_u32 s36, s36, s7
	s_subb_u32 s37, s37, 0
	global_load_dword v11, v177, s[36:37] offset:1024
	s_sub_u32 s36, s36, s7
	s_subb_u32 s37, s37, 0
	global_load_dword v12, v177, s[36:37] offset:1024
	s_sub_u32 s36, s36, s7
	s_subb_u32 s37, s37, 0
	global_load_dword v13, v177, s[36:37] offset:1024
	s_waitcnt vmcnt(52)
	v_readlane_b32 s40, v179, 40
	v_readlane_b32 s41, v179, 41
	v_readlane_b32 s42, v179, 42
	v_readlane_b32 s43, v179, 43
	v_readlane_b32 s44, v179, 44
	v_readlane_b32 s45, v179, 45
	v_readlane_b32 s46, v179, 46
	v_readlane_b32 s47, v179, 47
	v_fmac_f32_e32 v190, s40, v82
	v_fmac_f32_e32 v190, s41, v83
	v_fmac_f32_e32 v190, s42, v84
	v_fmac_f32_e32 v190, s43, v85
	v_fmac_f32_e32 v190, s44, v86
	v_fmac_f32_e32 v190, s45, v87
	v_fmac_f32_e32 v190, s46, v88
	v_fmac_f32_e32 v190, s47, v89
	s_sub_u32 s36, s36, s7
	s_subb_u32 s37, s37, 0
	global_load_dword v14, v177, s[36:37] offset:1024
	s_sub_u32 s36, s36, s7
	s_subb_u32 s37, s37, 0
	global_load_dword v15, v177, s[36:37] offset:1024
	s_sub_u32 s36, s36, s7
	s_subb_u32 s37, s37, 0
	global_load_dword v16, v177, s[36:37] offset:1024
	s_sub_u32 s36, s36, s7
	s_subb_u32 s37, s37, 0
	global_load_dword v17, v177, s[36:37] offset:1024
	s_sub_u32 s36, s36, s7
	s_subb_u32 s37, s37, 0
	global_load_dword v18, v177, s[36:37] offset:1024
	s_sub_u32 s36, s36, s7
	s_subb_u32 s37, s37, 0
	global_load_dword v19, v177, s[36:37] offset:1024
	s_sub_u32 s36, s36, s7
	s_subb_u32 s37, s37, 0
	global_load_dword v20, v177, s[36:37] offset:1024
	s_sub_u32 s36, s36, s7
	s_subb_u32 s37, s37, 0
	global_load_dword v21, v177, s[36:37] offset:1024
	s_waitcnt vmcnt(52)
	v_readlane_b32 s40, v179, 48
	v_readlane_b32 s41, v179, 49
	v_readlane_b32 s42, v179, 50
	v_readlane_b32 s43, v179, 51
	v_readlane_b32 s44, v179, 52
	v_readlane_b32 s45, v179, 53
	v_readlane_b32 s46, v179, 54
	v_readlane_b32 s47, v179, 55
	v_fmac_f32_e32 v190, s40, v90
	v_fmac_f32_e32 v190, s41, v91
	v_fmac_f32_e32 v190, s42, v92
	v_fmac_f32_e32 v190, s43, v93
	v_fmac_f32_e32 v190, s44, v94
	v_fmac_f32_e32 v190, s45, v95
	v_fmac_f32_e32 v190, s46, v96
	v_fmac_f32_e32 v190, s47, v97
	s_sub_u32 s36, s36, s7
	s_subb_u32 s37, s37, 0
	global_load_dword v22, v177, s[36:37] offset:1024
	s_sub_u32 s36, s36, s7
	s_subb_u32 s37, s37, 0
	global_load_dword v23, v177, s[36:37] offset:1024
	s_sub_u32 s36, s36, s7
	s_subb_u32 s37, s37, 0
	global_load_dword v24, v177, s[36:37] offset:1024
	s_sub_u32 s36, s36, s7
	s_subb_u32 s37, s37, 0
	global_load_dword v25, v177, s[36:37] offset:1024
	s_sub_u32 s36, s36, s7
	s_subb_u32 s37, s37, 0
	global_load_dword v26, v177, s[36:37] offset:1024
	s_sub_u32 s36, s36, s7
	s_subb_u32 s37, s37, 0
	global_load_dword v27, v177, s[36:37] offset:1024
	s_sub_u32 s36, s36, s7
	s_subb_u32 s37, s37, 0
	global_load_dword v28, v177, s[36:37] offset:1024
	s_sub_u32 s36, s36, s7
	s_subb_u32 s37, s37, 0
	global_load_dword v29, v177, s[36:37] offset:1024
	s_waitcnt vmcnt(52)
; __device__ __forceinline__ void attn_sample_item(const Args& a, const bf16_t* qkvb, bf16_t* og, float* lse, int it, int lane) {
;     ...
;     for (int j0 = 0; j0 < 128; j0 += 32) {
;         float v[32];
; #pragma unroll
;         for (int u = 0; u < 32; ++u) { const int idx = W + t - (j0 + u) * dil;
;             const float* vp = (idx < W ? cache + (size_t)idx * 512 : kvs + (size_t)(idx - 8) * 512) + 256; v[u] = vp[lane]; }
;         const float psrc = j0 < 64 ? p[0] : p[1];
; #pragma unroll
;         for (int u = 0; u < 32; ++u) o += __shfl(psrc, (j0 & 63) + u) * v[u];
;     }
;     o += __shfl(p[2], 0) * (cache + (size_t)t * 512 + 256)[lane];
	v_readlane_b32 s40, v179, 56
	v_readlane_b32 s41, v179, 57
	v_readlane_b32 s42, v179, 58
	v_readlane_b32 s43, v179, 59
	v_readlane_b32 s44, v179, 60
	v_readlane_b32 s45, v179, 61
	v_readlane_b32 s46, v179, 62
	v_readlane_b32 s47, v179, 63
	v_fmac_f32_e32 v190, s40, v98
	v_fmac_f32_e32 v190, s41, v99
	v_fmac_f32_e32 v190, s42, v100
	v_fmac_f32_e32 v190, s43, v101
	v_fmac_f32_e32 v190, s44, v102
	v_fmac_f32_e32 v190, s45, v103
	v_fmac_f32_e32 v190, s46, v104
	v_fmac_f32_e32 v190, s47, v105
	s_sub_u32 s36, s36, s7
	s_subb_u32 s37, s37, 0
	global_load_dword v30, v177, s[36:37] offset:1024
	s_sub_u32 s36, s36, s7
	s_subb_u32 s37, s37, 0
	global_load_dword v31, v177, s[36:37] offset:1024
	s_sub_u32 s36, s36, s7
	s_subb_u32 s37, s37, 0
	global_load_dword v32, v177, s[36:37] offset:1024
	s_sub_u32 s36, s36, s7
	s_subb_u32 s37, s37, 0
	global_load_dword v33, v177, s[36:37] offset:1024
	s_sub_u32 s36, s36, s7
	s_subb_u32 s37, s37, 0
	global_load_dword v34, v177, s[36:37] offset:1024
	s_sub_u32 s36, s36, s7
	s_subb_u32 s37, s37, 0
	global_load_dword v35, v177, s[36:37] offset:1024
	s_sub_u32 s36, s36, s7
	s_subb_u32 s37, s37, 0
	global_load_dword v36, v177, s[36:37] offset:1024
	s_sub_u32 s36, s36, s7
	s_subb_u32 s37, s37, 0
	global_load_dword v37, v177, s[36:37] offset:1024
	s_waitcnt vmcnt(52)
	v_readlane_b32 s40, v180, 0
	v_readlane_b32 s41, v180, 1
	v_readlane_b32 s42, v180, 2
	v_readlane_b32 s43, v180, 3
	v_readlane_b32 s44, v180, 4
	v_readlane_b32 s45, v180, 5
	v_readlane_b32 s46, v180, 6
	v_readlane_b32 s47, v180, 7
	v_fmac_f32_e32 v190, s40, v106
	v_fmac_f32_e32 v190, s41, v107
	v_fmac_f32_e32 v190, s42, v108
	v_fmac_f32_e32 v190, s43, v109
	v_fmac_f32_e32 v190, s44, v110
	v_fmac_f32_e32 v190, s45, v111
	v_fmac_f32_e32 v190, s46, v112
	v_fmac_f32_e32 v190, s47, v113
	s_sub_u32 s36, s36, s7
	s_subb_u32 s37, s37, 0
	global_load_dword v38, v177, s[36:37] offset:1024
	s_sub_u32 s36, s36, s7
	s_subb_u32 s37, s37, 0
	global_load_dword v39, v177, s[36:37] offset:1024
	s_sub_u32 s36, s36, s7
	s_subb_u32 s37, s37, 0
	global_load_dword v40, v177, s[36:37] offset:1024
	s_sub_u32 s36, s36, s7
	s_subb_u32 s37, s37, 0
	global_load_dword v41, v177, s[36:37] offset:1024
	s_sub_u32 s36, s36, s7
	s_subb_u32 s37, s37, 0
	global_load_dword v42, v177, s[36:37] offset:1024
	s_waitcnt vmcnt(49)
	v_readlane_b32 s40, v180, 8
	v_readlane_b32 s41, v180, 9
	v_readlane_b32 s42, v180, 10
	v_readlane_b32 s43, v180, 11
	v_readlane_b32 s44, v180, 12
	v_readlane_b32 s45, v180, 13
	v_readlane_b32 s46, v180, 14
	v_readlane_b32 s47, v180, 15
	v_fmac_f32_e32 v190, s40, v114
	v_fmac_f32_e32 v190, s41, v115
	v_fmac_f32_e32 v190, s42, v116
	v_fmac_f32_e32 v190, s43, v117
	v_fmac_f32_e32 v190, s44, v118
	v_fmac_f32_e32 v190, s45, v119
	v_fmac_f32_e32 v190, s46, v120
	v_fmac_f32_e32 v190, s47, v121
	s_waitcnt vmcnt(41)
	v_readlane_b32 s40, v180, 16
	v_readlane_b32 s41, v180, 17
	v_readlane_b32 s42, v180, 18
	v_readlane_b32 s43, v180, 19
	v_readlane_b32 s44, v180, 20
	v_readlane_b32 s45, v180, 21
	v_readlane_b32 s46, v180, 22
	v_readlane_b32 s47, v180, 23
	v_fmac_f32_e32 v190, s40, v122
	v_fmac_f32_e32 v190, s41, v123
	v_fmac_f32_e32 v190, s42, v124
	v_fmac_f32_e32 v190, s43, v125
	v_fmac_f32_e32 v190, s44, v126
	v_fmac_f32_e32 v190, s45, v127
	v_fmac_f32_e32 v190, s46, v0
	v_fmac_f32_e32 v190, s47, v1
	s_waitcnt vmcnt(33)
	v_readlane_b32 s40, v180, 24
	v_readlane_b32 s41, v180, 25
	v_readlane_b32 s42, v180, 26
	v_readlane_b32 s43, v180, 27
	v_readlane_b32 s44, v180, 28
	v_readlane_b32 s45, v180, 29
	v_readlane_b32 s46, v180, 30
	v_readlane_b32 s47, v180, 31
	v_fmac_f32_e32 v190, s40, v2
	v_fmac_f32_e32 v190, s41, v3
	v_fmac_f32_e32 v190, s42, v4
	v_fmac_f32_e32 v190, s43, v5
	v_fmac_f32_e32 v190, s44, v6
	v_fmac_f32_e32 v190, s45, v7
	v_fmac_f32_e32 v190, s46, v8
	v_fmac_f32_e32 v190, s47, v9
	s_waitcnt vmcnt(25)
; __device__ __forceinline__ unsigned cvt_pk_bf16(float lo, float hi) { unsigned r; asm volatile("v_cvt_pk_bf16_f32 %0, %1, %2" : "=v"(r) : "v"(lo), "v"(hi)); return r; }
; __device__ __forceinline__ void attn_sample_item(const Args& a, const bf16_t* qkvb, bf16_t* og, float* lse, int it, int lane) {
;     ...
; #pragma unroll
;         for (int u = 0; u < 32; ++u) o += __shfl(psrc, (j0 & 63) + u) * v[u];
;     }
;     o += __shfl(p[2], 0) * (cache + (size_t)t * 512 + 256)[lane];
;     og[(size_t)row * AW + g * 256 + hh * 64 + lane] = (bf16_t)(cvt_pk_bf16(o / den, 0.f) & 0xffffu);
;     if (lane == 0) lse[(size_t)row * 12 + g * 4 + hh] = mx + __logf(den);
; }
	v_readlane_b32 s40, v180, 32
	v_readlane_b32 s41, v180, 33
	v_readlane_b32 s42, v180, 34
	v_readlane_b32 s43, v180, 35
	v_readlane_b32 s44, v180, 36
	v_readlane_b32 s45, v180, 37
	v_readlane_b32 s46, v180, 38
	v_readlane_b32 s47, v180, 39
	v_fmac_f32_e32 v190, s40, v10
	v_fmac_f32_e32 v190, s41, v11
	v_fmac_f32_e32 v190, s42, v12
	v_fmac_f32_e32 v190, s43, v13
	v_fmac_f32_e32 v190, s44, v14
	v_fmac_f32_e32 v190, s45, v15
	v_fmac_f32_e32 v190, s46, v16
	v_fmac_f32_e32 v190, s47, v17
	s_waitcnt vmcnt(17)
	v_readlane_b32 s40, v180, 40
	v_readlane_b32 s41, v180, 41
	v_readlane_b32 s42, v180, 42
	v_readlane_b32 s43, v180, 43
	v_readlane_b32 s44, v180, 44
	v_readlane_b32 s45, v180, 45
	v_readlane_b32 s46, v180, 46
	v_readlane_b32 s47, v180, 47
	v_fmac_f32_e32 v190, s40, v18
	v_fmac_f32_e32 v190, s41, v19
	v_fmac_f32_e32 v190, s42, v20
	v_fmac_f32_e32 v190, s43, v21
	v_fmac_f32_e32 v190, s44, v22
	v_fmac_f32_e32 v190, s45, v23
	v_fmac_f32_e32 v190, s46, v24
	v_fmac_f32_e32 v190, s47, v25
	s_waitcnt vmcnt(9)
	v_readlane_b32 s40, v180, 48
	v_readlane_b32 s41, v180, 49
	v_readlane_b32 s42, v180, 50
	v_readlane_b32 s43, v180, 51
	v_readlane_b32 s44, v180, 52
	v_readlane_b32 s45, v180, 53
	v_readlane_b32 s46, v180, 54
	v_readlane_b32 s47, v180, 55
	v_fmac_f32_e32 v190, s40, v26
	v_fmac_f32_e32 v190, s41, v27
	v_fmac_f32_e32 v190, s42, v28
	v_fmac_f32_e32 v190, s43, v29
	v_fmac_f32_e32 v190, s44, v30
	v_fmac_f32_e32 v190, s45, v31
	v_fmac_f32_e32 v190, s46, v32
	v_fmac_f32_e32 v190, s47, v33
	s_waitcnt vmcnt(1)
	v_readlane_b32 s40, v180, 56
	v_readlane_b32 s41, v180, 57
	v_readlane_b32 s42, v180, 58
	v_readlane_b32 s43, v180, 59
	v_readlane_b32 s44, v180, 60
	v_readlane_b32 s45, v180, 61
	v_readlane_b32 s46, v180, 62
	v_readlane_b32 s47, v180, 63
	v_fmac_f32_e32 v190, s40, v34
	v_fmac_f32_e32 v190, s41, v35
	v_fmac_f32_e32 v190, s42, v36
	v_fmac_f32_e32 v190, s43, v37
	v_fmac_f32_e32 v190, s44, v38
	v_fmac_f32_e32 v190, s45, v39
	v_fmac_f32_e32 v190, s46, v40
	v_fmac_f32_e32 v190, s47, v41
	s_waitcnt vmcnt(0)
	v_readlane_b32 s40, v181, 0
	s_nop 1
	v_fmac_f32_e32 v190, s40, v42
	v_div_scale_f32 v185, s[6:7], v189, v189, v190
	v_rcp_f32_e32 v186, v185
	v_div_scale_f32 v187, vcc, v190, v189, v190
	v_fma_f32 v191, -v185, v186, 1.0
	v_fmac_f32_e32 v186, v191, v186
	v_mul_f32_e32 v191, v187, v186
	v_fma_f32 v182, -v185, v191, v187
	v_fmac_f32_e32 v191, v182, v186
	v_fma_f32 v185, -v185, v191, v187
	v_div_fmas_f32 v185, v185, v186, v191
	v_div_fixup_f32 v185, v185, v189, v190
	v_cvt_pk_bf16_f32 v185, v185, v178
	s_load_dwordx2 s[80:81], s[0:1], 0xd0
	s_bfe_u32 s4, s60, 0x20003
	s_lshr_b32 s6, s60, 5
	s_mul_hi_u32 s7, s6, 0x55555556
	s_mul_i32 s7, s7, 3
	s_sub_u32 s36, s6, s7
	s_mul_i32 s6, s73, 0x300
	s_lshl_b32 s7, s36, 8
	s_add_u32 s6, s6, s7
	s_lshl_b32 s7, s4, 6
	s_add_u32 s6, s6, s7
	s_lshl_b32 s6, s6, 1
	s_add_u32 s6, s6, 0x108e0000
	s_mul_i32 s7, s73, 12
	s_lshl_b32 s37, s36, 2
	s_add_u32 s7, s7, s37
	s_add_u32 s7, s7, s4
	s_lshl_b32 s7, s7, 2
	s_add_u32 s7, s7, 0x139a0000
	v_lshlrev_b32_e32 v191, 1, v192
	s_waitcnt lgkmcnt(0)
	s_add_u32 s36, s80, s6
	s_addc_u32 s37, s81, 0
	global_store_short v191, v185, s[36:37]
	v_log_f32_e32 v185, v189
	s_mov_b32 s4, 0x3f317217
	v_mul_f32_e32 v186, 0x3f317217, v185
	v_fma_f32 v186, v185, s4, -v186
	v_fmac_f32_e32 v186, 0x3377d1cf, v185
	v_fmac_f32_e32 v186, 0x3f317217, v185
	v_add_f32_e32 v186, v188, v186
	s_add_u32 s36, s80, s7
	s_addc_u32 s37, s81, 0
	s_mov_b64 s[6:7], exec
	s_mov_b64 exec, 1
	global_store_dword v178, v186, s[36:37]
	s_mov_b64 exec, s[6:7]
	s_add_u32 s60, s60, s62
	s_cmpk_lt_u32 s60, 0xc00
	s_cbranch_scc1 .Latts_item

; __global__ void __launch_bounds__(NTHREADS, 2) fwd_megakernel(Args a) {
;     ...
;     _Pragma("unroll") for (int rep = 0; rep < REP_FINAL; ++rep) {
;         const float* gf = a.in[7]; const float* ssq6 = SSQ(6);
;         for (int row = blockIdx.x * NWAVES + wave; row < MT; row += gridDim.x * NWAVES) {
;             const float s = row_scale(ssq6, row);
; #pragma unroll
;             for (int j = 0; j < 2; ++j) { const int col = 512 * j + 8 * lane; const u32x4 r = *(const u32x4*)(xb + (size_t)row * D + col);
;                 const f32x4 g0 = *(const f32x4*)(gf + col), g1 = *(const f32x4*)(gf + col + 4); f32x4 v0, v1;
;                 v0[0] = __uint_as_float(r.x << 16); v0[1] = __uint_as_float(r.x & 0xffff0000u); v0[2] = __uint_as_float(r.y << 16); v0[3] = __uint_as_float(r.y & 0xffff0000u);
;                 v1[0] = __uint_as_float(r.z << 16); v1[1] = __uint_as_float(r.z & 0xffff0000u); v1[2] = __uint_as_float(r.w << 16); v1[3] = __uint_as_float(r.w & 0xffff0000u);
;                 *(f32x4*)(a.out + O_Y + (size_t)row * D + col) = v0 * s * g0; *(f32x4*)(a.out + O_Y + (size_t)row * D + col + 4) = v1 * s * g1; }
.LBB0_2022:
	s_or_b64 exec, exec, s[2:3]
	v_readlane_b32 s2, v243, 4
	v_readlane_b32 s3, v243, 5
	s_andn2_b64 vcc, exec, s[2:3]
	s_waitcnt lgkmcnt(0)
	s_barrier
	s_cbranch_vccnz .LBB0_2025
	s_load_dwordx2 s[2:3], s[0:1], 0x38
	s_load_dwordx2 s[4:5], s[0:1], 0xc8
	s_load_dwordx2 s[12:13], s[0:1], 0xd0
	v_mbcnt_lo_u32_b32 v0, -1, 0
	v_mbcnt_hi_u32_b32 v0, -1, v0
	v_mov_b32_e32 v1, 0
	v_lshlrev_b32_e32 v2, 3, v0
	v_lshlrev_b32_e32 v3, 4, v0
	s_mov_b32 s14, 0x800000
	s_waitcnt lgkmcnt(0)
	s_add_u32 s10, s12, 0x14ff8000
	s_addc_u32 s11, s13, 0
	s_add_u32 s12, s12, 0x4e00000
	s_addc_u32 s13, s13, 0
	global_load_dwordx4 v[16:19], v3, s[2:3]
	global_load_dwordx4 v[20:23], v3, s[2:3] offset:1024
	global_load_dwordx4 v[24:27], v3, s[2:3] offset:2048
	global_load_dwordx4 v[28:31], v3, s[2:3] offset:3072
	s_mov_b32 s40, s64
	s_lshl_b32 s6, s40, 6
	s_add_u32 s6, s10, s6
	s_addc_u32 s7, s11, 0
	s_lshl_b32 s8, s40, 11
	s_add_u32 s8, s12, s8
	s_addc_u32 s9, s13, 0
	global_load_dwordx4 v[32:35], v1, s[6:7]
	global_load_dwordx4 v[36:39], v1, s[6:7] offset:16
	global_load_dwordx4 v[40:43], v1, s[6:7] offset:32
	global_load_dwordx4 v[44:47], v1, s[6:7] offset:48
	global_load_dwordx2 v[48:49], v2, s[8:9]
	global_load_dwordx2 v[50:51], v2, s[8:9] offset:512
	global_load_dwordx2 v[52:53], v2, s[8:9] offset:1024
	global_load_dwordx2 v[54:55], v2, s[8:9] offset:1536
	s_add_u32 s41, s40, s62
	s_cmpk_lt_u32 s41, 16640
	s_cbranch_scc0 .Lfin_lastA
	s_lshl_b32 s6, s41, 6
	s_add_u32 s6, s10, s6
	s_addc_u32 s7, s11, 0
	s_lshl_b32 s8, s41, 11
	s_add_u32 s8, s12, s8
	s_addc_u32 s9, s13, 0
	global_load_dwordx4 v[56:59], v1, s[6:7]
	global_load_dwordx4 v[60:63], v1, s[6:7] offset:16
	global_load_dwordx4 v[64:67], v1, s[6:7] offset:32
	global_load_dwordx4 v[68:71], v1, s[6:7] offset:48
	global_load_dwordx2 v[72:73], v2, s[8:9]
	global_load_dwordx2 v[74:75], v2, s[8:9] offset:512
	global_load_dwordx2 v[76:77], v2, s[8:9] offset:1024
	global_load_dwordx2 v[78:79], v2, s[8:9] offset:1536
	s_waitcnt vmcnt(8)
	v_add_f32_e32 v4, v32, v33
	v_add_f32_e32 v5, v34, v35
	v_add_f32_e32 v4, v4, v5
	v_add_f32_e32 v6, v36, v37
	v_add_f32_e32 v7, v38, v39
	v_add_f32_e32 v6, v6, v7
	v_add_f32_e32 v8, v40, v41
	v_add_f32_e32 v9, v42, v43
	v_add_f32_e32 v8, v8, v9
	v_add_f32_e32 v10, v44, v45
	v_add_f32_e32 v11, v46, v47
	v_add_f32_e32 v10, v10, v11
	v_add_f32_e32 v4, v4, v6
	v_add_f32_e32 v8, v8, v10
	v_add_f32_e32 v4, v4, v8
	v_mov_b32_e32 v5, 0x358637bd
	v_fmac_f32_e32 v5, 0x3a800000, v4
	v_mul_f32_e32 v6, 0x4b800000, v5
	v_cmp_gt_f32_e32 vcc, s14, v5
	s_nop 1
	v_cndmask_b32_e32 v5, v5, v6, vcc
	v_rsq_f32_e32 v5, v5
	s_nop 0
	v_mul_f32_e32 v6, 0x45800000, v5
	v_cndmask_b32_e32 v5, v5, v6, vcc
	s_lshl_b32 s6, s40, 12
	s_add_u32 s6, s4, s6
	s_addc_u32 s7, s5, 0
	v_lshlrev_b32_e32 v6, 16, v48
	v_and_b32_e32 v7, 0xffff0000, v48
	v_lshlrev_b32_e32 v8, 16, v49
	v_and_b32_e32 v9, 0xffff0000, v49
	v_mul_f32_e32 v6, v5, v6
	v_mul_f32_e32 v80, v16, v6
	v_mul_f32_e32 v7, v5, v7
	v_mul_f32_e32 v81, v17, v7
	v_mul_f32_e32 v8, v5, v8
	v_mul_f32_e32 v82, v18, v8
	v_mul_f32_e32 v9, v5, v9
	v_mul_f32_e32 v83, v19, v9
	global_store_dwordx4 v3, v[80:83], s[6:7]
	v_lshlrev_b32_e32 v6, 16, v50
	v_and_b32_e32 v7, 0xffff0000, v50
	v_lshlrev_b32_e32 v8, 16, v51
	v_and_b32_e32 v9, 0xffff0000, v51
	v_mul_f32_e32 v6, v5, v6
	v_mul_f32_e32 v84, v20, v6
	v_mul_f32_e32 v7, v5, v7
	v_mul_f32_e32 v85, v21, v7
	v_mul_f32_e32 v8, v5, v8
	v_mul_f32_e32 v86, v22, v8
	v_mul_f32_e32 v9, v5, v9
	v_mul_f32_e32 v87, v23, v9
	global_store_dwordx4 v3, v[84:87], s[6:7] offset:1024
	v_lshlrev_b32_e32 v6, 16, v52
	v_and_b32_e32 v7, 0xffff0000, v52
	v_lshlrev_b32_e32 v8, 16, v53
	v_and_b32_e32 v9, 0xffff0000, v53
	v_mul_f32_e32 v6, v5, v6
	v_mul_f32_e32 v88, v24, v6
	v_mul_f32_e32 v7, v5, v7
	v_mul_f32_e32 v89, v25, v7
	v_mul_f32_e32 v8, v5, v8
	v_mul_f32_e32 v90, v26, v8
	v_mul_f32_e32 v9, v5, v9
	v_mul_f32_e32 v91, v27, v9
	global_store_dwordx4 v3, v[88:91], s[6:7] offset:2048
	v_lshlrev_b32_e32 v6, 16, v54
	v_and_b32_e32 v7, 0xffff0000, v54
	v_lshlrev_b32_e32 v8, 16, v55
	v_and_b32_e32 v9, 0xffff0000, v55
	v_mul_f32_e32 v6, v5, v6
	v_mul_f32_e32 v92, v28, v6
	v_mul_f32_e32 v7, v5, v7
	v_mul_f32_e32 v93, v29, v7
	v_mul_f32_e32 v8, v5, v8
	v_mul_f32_e32 v94, v30, v8
	v_mul_f32_e32 v9, v5, v9
	v_mul_f32_e32 v95, v31, v9
	global_store_dwordx4 v3, v[92:95], s[6:7] offset:3072
; __global__ void __launch_bounds__(NTHREADS, 2) fwd_megakernel(Args a) {
;     ...
;         for (int row = blockIdx.x * NWAVES + wave; row < MT; row += gridDim.x * NWAVES) {
;             const float s = row_scale(ssq6, row);
; #pragma unroll
;             for (int j = 0; j < 2; ++j) { const int col = 512 * j + 8 * lane; const u32x4 r = *(const u32x4*)(xb + (size_t)row * D + col);
;                 const f32x4 g0 = *(const f32x4*)(gf + col), g1 = *(const f32x4*)(gf + col + 4); f32x4 v0, v1;
;                 v0[0] = __uint_as_float(r.x << 16); v0[1] = __uint_as_float(r.x & 0xffff0000u); v0[2] = __uint_as_float(r.y << 16); v0[3] = __uint_as_float(r.y & 0xffff0000u);
;                 v1[0] = __uint_as_float(r.z << 16); v1[1] = __uint_as_float(r.z & 0xffff0000u); v1[2] = __uint_as_float(r.w << 16); v1[3] = __uint_as_float(r.w & 0xffff0000u);
;                 *(f32x4*)(a.out + O_Y + (size_t)row * D + col) = v0 * s * g0; *(f32x4*)(a.out + O_Y + (size_t)row * D + col + 4) = v1 * s * g1; }
;         }
.Lfin_loop:
	s_add_u32 s40, s41, s62
	s_cmpk_lt_u32 s40, 16640
	s_cbranch_scc0 .Lfin_lastB
	s_lshl_b32 s6, s40, 6
	s_add_u32 s6, s10, s6
	s_addc_u32 s7, s11, 0
	s_lshl_b32 s8, s40, 11
	s_add_u32 s8, s12, s8
	s_addc_u32 s9, s13, 0
	global_load_dwordx4 v[32:35], v1, s[6:7]
	global_load_dwordx4 v[36:39], v1, s[6:7] offset:16
	global_load_dwordx4 v[40:43], v1, s[6:7] offset:32
	global_load_dwordx4 v[44:47], v1, s[6:7] offset:48
	global_load_dwordx2 v[48:49], v2, s[8:9]
	global_load_dwordx2 v[50:51], v2, s[8:9] offset:512
	global_load_dwordx2 v[52:53], v2, s[8:9] offset:1024
	global_load_dwordx2 v[54:55], v2, s[8:9] offset:1536
	s_waitcnt vmcnt(12)
	v_add_f32_e32 v4, v56, v57
	v_add_f32_e32 v5, v58, v59
	v_add_f32_e32 v4, v4, v5
	v_add_f32_e32 v6, v60, v61
	v_add_f32_e32 v7, v62, v63
	v_add_f32_e32 v6, v6, v7
	v_add_f32_e32 v8, v64, v65
	v_add_f32_e32 v9, v66, v67
	v_add_f32_e32 v8, v8, v9
	v_add_f32_e32 v10, v68, v69
	v_add_f32_e32 v11, v70, v71
	v_add_f32_e32 v10, v10, v11
	v_add_f32_e32 v4, v4, v6
	v_add_f32_e32 v8, v8, v10
	v_add_f32_e32 v4, v4, v8
	v_mov_b32_e32 v5, 0x358637bd
	v_fmac_f32_e32 v5, 0x3a800000, v4
	v_mul_f32_e32 v6, 0x4b800000, v5
	v_cmp_gt_f32_e32 vcc, s14, v5
	s_nop 1
	v_cndmask_b32_e32 v5, v5, v6, vcc
	v_rsq_f32_e32 v5, v5
	s_nop 0
	v_mul_f32_e32 v6, 0x45800000, v5
	v_cndmask_b32_e32 v5, v5, v6, vcc
	s_lshl_b32 s6, s41, 12
	s_add_u32 s6, s4, s6
	s_addc_u32 s7, s5, 0
	v_lshlrev_b32_e32 v6, 16, v72
	v_and_b32_e32 v7, 0xffff0000, v72
	v_lshlrev_b32_e32 v8, 16, v73
	v_and_b32_e32 v9, 0xffff0000, v73
	v_mul_f32_e32 v6, v5, v6
	v_mul_f32_e32 v96, v16, v6
	v_mul_f32_e32 v7, v5, v7
	v_mul_f32_e32 v97, v17, v7
	v_mul_f32_e32 v8, v5, v8
	v_mul_f32_e32 v98, v18, v8
	v_mul_f32_e32 v9, v5, v9
	v_mul_f32_e32 v99, v19, v9
	global_store_dwordx4 v3, v[96:99], s[6:7]
	v_lshlrev_b32_e32 v6, 16, v74
	v_and_b32_e32 v7, 0xffff0000, v74
	v_lshlrev_b32_e32 v8, 16, v75
	v_and_b32_e32 v9, 0xffff0000, v75
	v_mul_f32_e32 v6, v5, v6
	v_mul_f32_e32 v100, v20, v6
	v_mul_f32_e32 v7, v5, v7
	v_mul_f32_e32 v101, v21, v7
	v_mul_f32_e32 v8, v5, v8
	v_mul_f32_e32 v102, v22, v8
	v_mul_f32_e32 v9, v5, v9
	v_mul_f32_e32 v103, v23, v9
	global_store_dwordx4 v3, v[100:103], s[6:7] offset:1024
	v_lshlrev_b32_e32 v6, 16, v76
	v_and_b32_e32 v7, 0xffff0000, v76
	v_lshlrev_b32_e32 v8, 16, v77
	v_and_b32_e32 v9, 0xffff0000, v77
	v_mul_f32_e32 v6, v5, v6
	v_mul_f32_e32 v104, v24, v6
	v_mul_f32_e32 v7, v5, v7
	v_mul_f32_e32 v105, v25, v7
	v_mul_f32_e32 v8, v5, v8
	v_mul_f32_e32 v106, v26, v8
	v_mul_f32_e32 v9, v5, v9
	v_mul_f32_e32 v107, v27, v9
	global_store_dwordx4 v3, v[104:107], s[6:7] offset:2048
	v_lshlrev_b32_e32 v6, 16, v78
	v_and_b32_e32 v7, 0xffff0000, v78
	v_lshlrev_b32_e32 v8, 16, v79
	v_and_b32_e32 v9, 0xffff0000, v79
	v_mul_f32_e32 v6, v5, v6
	v_mul_f32_e32 v108, v28, v6
	v_mul_f32_e32 v7, v5, v7
	v_mul_f32_e32 v109, v29, v7
	v_mul_f32_e32 v8, v5, v8
	v_mul_f32_e32 v110, v30, v8
	v_mul_f32_e32 v9, v5, v9
	v_mul_f32_e32 v111, v31, v9
	global_store_dwordx4 v3, v[108:111], s[6:7] offset:3072
	s_add_u32 s41, s40, s62
	s_cmpk_lt_u32 s41, 16640
	s_cbranch_scc0 .Lfin_lastA
	s_lshl_b32 s6, s41, 6
	s_add_u32 s6, s10, s6
	s_addc_u32 s7, s11, 0
	s_lshl_b32 s8, s41, 11
	s_add_u32 s8, s12, s8
	s_addc_u32 s9, s13, 0
	global_load_dwordx4 v[56:59], v1, s[6:7]
	global_load_dwordx4 v[60:63], v1, s[6:7] offset:16
	global_load_dwordx4 v[64:67], v1, s[6:7] offset:32
	global_load_dwordx4 v[68:71], v1, s[6:7] offset:48
	global_load_dwordx2 v[72:73], v2, s[8:9]
	global_load_dwordx2 v[74:75], v2, s[8:9] offset:512
	global_load_dwordx2 v[76:77], v2, s[8:9] offset:1024
	global_load_dwordx2 v[78:79], v2, s[8:9] offset:1536
	s_waitcnt vmcnt(12)
	v_add_f32_e32 v4, v32, v33
	v_add_f32_e32 v5, v34, v35
	v_add_f32_e32 v4, v4, v5
	v_add_f32_e32 v6, v36, v37
	v_add_f32_e32 v7, v38, v39
	v_add_f32_e32 v6, v6, v7
	v_add_f32_e32 v8, v40, v41
	v_add_f32_e32 v9, v42, v43
	v_add_f32_e32 v8, v8, v9
	v_add_f32_e32 v10, v44, v45
	v_add_f32_e32 v11, v46, v47
	v_add_f32_e32 v10, v10, v11
	v_add_f32_e32 v4, v4, v6
	v_add_f32_e32 v8, v8, v10
	v_add_f32_e32 v4, v4, v8
	v_mov_b32_e32 v5, 0x358637bd
	v_fmac_f32_e32 v5, 0x3a800000, v4
	v_mul_f32_e32 v6, 0x4b800000, v5
	v_cmp_gt_f32_e32 vcc, s14, v5
	s_nop 1
	v_cndmask_b32_e32 v5, v5, v6, vcc
	v_rsq_f32_e32 v5, v5
	s_nop 0
	v_mul_f32_e32 v6, 0x45800000, v5
	v_cndmask_b32_e32 v5, v5, v6, vcc
	s_lshl_b32 s6, s40, 12
	s_add_u32 s6, s4, s6
	s_addc_u32 s7, s5, 0
	v_lshlrev_b32_e32 v6, 16, v48
	v_and_b32_e32 v7, 0xffff0000, v48
	v_lshlrev_b32_e32 v8, 16, v49
	v_and_b32_e32 v9, 0xffff0000, v49
	v_mul_f32_e32 v6, v5, v6
	v_mul_f32_e32 v80, v16, v6
	v_mul_f32_e32 v7, v5, v7
	v_mul_f32_e32 v81, v17, v7
	v_mul_f32_e32 v8, v5, v8
	v_mul_f32_e32 v82, v18, v8
	v_mul_f32_e32 v9, v5, v9
	v_mul_f32_e32 v83, v19, v9
	global_store_dwordx4 v3, v[80:83], s[6:7]
	v_lshlrev_b32_e32 v6, 16, v50
	v_and_b32_e32 v7, 0xffff0000, v50
	v_lshlrev_b32_e32 v8, 16, v51
	v_and_b32_e32 v9, 0xffff0000, v51
	v_mul_f32_e32 v6, v5, v6
	v_mul_f32_e32 v84, v20, v6
	v_mul_f32_e32 v7, v5, v7
	v_mul_f32_e32 v85, v21, v7
	v_mul_f32_e32 v8, v5, v8
	v_mul_f32_e32 v86, v22, v8
	v_mul_f32_e32 v9, v5, v9
	v_mul_f32_e32 v87, v23, v9
	global_store_dwordx4 v3, v[84:87], s[6:7] offset:1024
	v_lshlrev_b32_e32 v6, 16, v52
	v_and_b32_e32 v7, 0xffff0000, v52
	v_lshlrev_b32_e32 v8, 16, v53
	v_and_b32_e32 v9, 0xffff0000, v53
	v_mul_f32_e32 v6, v5, v6
	v_mul_f32_e32 v88, v24, v6
	v_mul_f32_e32 v7, v5, v7
	v_mul_f32_e32 v89, v25, v7
	v_mul_f32_e32 v8, v5, v8
	v_mul_f32_e32 v90, v26, v8
	v_mul_f32_e32 v9, v5, v9
	v_mul_f32_e32 v91, v27, v9
	global_store_dwordx4 v3, v[88:91], s[6:7] offset:2048
	v_lshlrev_b32_e32 v6, 16, v54
	v_and_b32_e32 v7, 0xffff0000, v54
	v_lshlrev_b32_e32 v8, 16, v55
	v_and_b32_e32 v9, 0xffff0000, v55
	v_mul_f32_e32 v6, v5, v6
	v_mul_f32_e32 v92, v28, v6
	v_mul_f32_e32 v7, v5, v7
	v_mul_f32_e32 v93, v29, v7
	v_mul_f32_e32 v8, v5, v8
	v_mul_f32_e32 v94, v30, v8
	v_mul_f32_e32 v9, v5, v9
	v_mul_f32_e32 v95, v31, v9
	global_store_dwordx4 v3, v[92:95], s[6:7] offset:3072
	s_branch .Lfin_loop
; __global__ void __launch_bounds__(NTHREADS, 2) fwd_megakernel(Args a) {
;     ...
;         for (int row = blockIdx.x * NWAVES + wave; row < MT; row += gridDim.x * NWAVES) {
;             const float s = row_scale(ssq6, row);
; #pragma unroll
;             for (int j = 0; j < 2; ++j) { const int col = 512 * j + 8 * lane; const u32x4 r = *(const u32x4*)(xb + (size_t)row * D + col);
;                 const f32x4 g0 = *(const f32x4*)(gf + col), g1 = *(const f32x4*)(gf + col + 4); f32x4 v0, v1;
;                 v0[0] = __uint_as_float(r.x << 16); v0[1] = __uint_as_float(r.x & 0xffff0000u); v0[2] = __uint_as_float(r.y << 16); v0[3] = __uint_as_float(r.y & 0xffff0000u);
;                 v1[0] = __uint_as_float(r.z << 16); v1[1] = __uint_as_float(r.z & 0xffff0000u); v1[2] = __uint_as_float(r.w << 16); v1[3] = __uint_as_float(r.w & 0xffff0000u);
;                 *(f32x4*)(a.out + O_Y + (size_t)row * D + col) = v0 * s * g0; *(f32x4*)(a.out + O_Y + (size_t)row * D + col + 4) = v1 * s * g1; }
;         }
.Lfin_lastA:
	s_waitcnt vmcnt(0)
	v_add_f32_e32 v4, v32, v33
	v_add_f32_e32 v5, v34, v35
	v_add_f32_e32 v4, v4, v5
	v_add_f32_e32 v6, v36, v37
	v_add_f32_e32 v7, v38, v39
	v_add_f32_e32 v6, v6, v7
	v_add_f32_e32 v8, v40, v41
	v_add_f32_e32 v9, v42, v43
	v_add_f32_e32 v8, v8, v9
	v_add_f32_e32 v10, v44, v45
	v_add_f32_e32 v11, v46, v47
	v_add_f32_e32 v10, v10, v11
	v_add_f32_e32 v4, v4, v6
	v_add_f32_e32 v8, v8, v10
	v_add_f32_e32 v4, v4, v8
	v_mov_b32_e32 v5, 0x358637bd
	v_fmac_f32_e32 v5, 0x3a800000, v4
	v_mul_f32_e32 v6, 0x4b800000, v5
	v_cmp_gt_f32_e32 vcc, s14, v5
	s_nop 1
	v_cndmask_b32_e32 v5, v5, v6, vcc
	v_rsq_f32_e32 v5, v5
	s_nop 0
	v_mul_f32_e32 v6, 0x45800000, v5
	v_cndmask_b32_e32 v5, v5, v6, vcc
	s_lshl_b32 s6, s40, 12
	s_add_u32 s6, s4, s6
	s_addc_u32 s7, s5, 0
	v_lshlrev_b32_e32 v6, 16, v48
	v_and_b32_e32 v7, 0xffff0000, v48
	v_lshlrev_b32_e32 v8, 16, v49
	v_and_b32_e32 v9, 0xffff0000, v49
	v_mul_f32_e32 v6, v5, v6
	v_mul_f32_e32 v80, v16, v6
	v_mul_f32_e32 v7, v5, v7
	v_mul_f32_e32 v81, v17, v7
	v_mul_f32_e32 v8, v5, v8
	v_mul_f32_e32 v82, v18, v8
	v_mul_f32_e32 v9, v5, v9
	v_mul_f32_e32 v83, v19, v9
	global_store_dwordx4 v3, v[80:83], s[6:7]
	v_lshlrev_b32_e32 v6, 16, v50
	v_and_b32_e32 v7, 0xffff0000, v50
	v_lshlrev_b32_e32 v8, 16, v51
	v_and_b32_e32 v9, 0xffff0000, v51
	v_mul_f32_e32 v6, v5, v6
	v_mul_f32_e32 v84, v20, v6
	v_mul_f32_e32 v7, v5, v7
	v_mul_f32_e32 v85, v21, v7
	v_mul_f32_e32 v8, v5, v8
	v_mul_f32_e32 v86, v22, v8
	v_mul_f32_e32 v9, v5, v9
	v_mul_f32_e32 v87, v23, v9
	global_store_dwordx4 v3, v[84:87], s[6:7] offset:1024
	v_lshlrev_b32_e32 v6, 16, v52
	v_and_b32_e32 v7, 0xffff0000, v52
	v_lshlrev_b32_e32 v8, 16, v53
	v_and_b32_e32 v9, 0xffff0000, v53
	v_mul_f32_e32 v6, v5, v6
	v_mul_f32_e32 v88, v24, v6
	v_mul_f32_e32 v7, v5, v7
	v_mul_f32_e32 v89, v25, v7
	v_mul_f32_e32 v8, v5, v8
	v_mul_f32_e32 v90, v26, v8
	v_mul_f32_e32 v9, v5, v9
	v_mul_f32_e32 v91, v27, v9
	global_store_dwordx4 v3, v[88:91], s[6:7] offset:2048
	v_lshlrev_b32_e32 v6, 16, v54
	v_and_b32_e32 v7, 0xffff0000, v54
	v_lshlrev_b32_e32 v8, 16, v55
	v_and_b32_e32 v9, 0xffff0000, v55
	v_mul_f32_e32 v6, v5, v6
	v_mul_f32_e32 v92, v28, v6
	v_mul_f32_e32 v7, v5, v7
	v_mul_f32_e32 v93, v29, v7
	v_mul_f32_e32 v8, v5, v8
	v_mul_f32_e32 v94, v30, v8
	v_mul_f32_e32 v9, v5, v9
	v_mul_f32_e32 v95, v31, v9
	global_store_dwordx4 v3, v[92:95], s[6:7] offset:3072
	s_branch .LBB0_2025
.Lfin_lastB:
	s_waitcnt vmcnt(0)
	v_add_f32_e32 v4, v56, v57
	v_add_f32_e32 v5, v58, v59
	v_add_f32_e32 v4, v4, v5
	v_add_f32_e32 v6, v60, v61
	v_add_f32_e32 v7, v62, v63
	v_add_f32_e32 v6, v6, v7
	v_add_f32_e32 v8, v64, v65
	v_add_f32_e32 v9, v66, v67
	v_add_f32_e32 v8, v8, v9
	v_add_f32_e32 v10, v68, v69
	v_add_f32_e32 v11, v70, v71
	v_add_f32_e32 v10, v10, v11
	v_add_f32_e32 v4, v4, v6
	v_add_f32_e32 v8, v8, v10
	v_add_f32_e32 v4, v4, v8
	v_mov_b32_e32 v5, 0x358637bd
	v_fmac_f32_e32 v5, 0x3a800000, v4
	v_mul_f32_e32 v6, 0x4b800000, v5
	v_cmp_gt_f32_e32 vcc, s14, v5
	s_nop 1
	v_cndmask_b32_e32 v5, v5, v6, vcc
	v_rsq_f32_e32 v5, v5
	s_nop 0
	v_mul_f32_e32 v6, 0x45800000, v5
	v_cndmask_b32_e32 v5, v5, v6, vcc
	s_lshl_b32 s6, s41, 12
	s_add_u32 s6, s4, s6
	s_addc_u32 s7, s5, 0
	v_lshlrev_b32_e32 v6, 16, v72
	v_and_b32_e32 v7, 0xffff0000, v72
	v_lshlrev_b32_e32 v8, 16, v73
	v_and_b32_e32 v9, 0xffff0000, v73
	v_mul_f32_e32 v6, v5, v6
	v_mul_f32_e32 v96, v16, v6
	v_mul_f32_e32 v7, v5, v7
	v_mul_f32_e32 v97, v17, v7
	v_mul_f32_e32 v8, v5, v8
	v_mul_f32_e32 v98, v18, v8
	v_mul_f32_e32 v9, v5, v9
	v_mul_f32_e32 v99, v19, v9
	global_store_dwordx4 v3, v[96:99], s[6:7]
	v_lshlrev_b32_e32 v6, 16, v74
	v_and_b32_e32 v7, 0xffff0000, v74
	v_lshlrev_b32_e32 v8, 16, v75
	v_and_b32_e32 v9, 0xffff0000, v75
	v_mul_f32_e32 v6, v5, v6
	v_mul_f32_e32 v100, v20, v6
	v_mul_f32_e32 v7, v5, v7
	v_mul_f32_e32 v101, v21, v7
	v_mul_f32_e32 v8, v5, v8
	v_mul_f32_e32 v102, v22, v8
	v_mul_f32_e32 v9, v5, v9
	v_mul_f32_e32 v103, v23, v9
	global_store_dwordx4 v3, v[100:103], s[6:7] offset:1024
	v_lshlrev_b32_e32 v6, 16, v76
	v_and_b32_e32 v7, 0xffff0000, v76
	v_lshlrev_b32_e32 v8, 16, v77
	v_and_b32_e32 v9, 0xffff0000, v77
	v_mul_f32_e32 v6, v5, v6
	v_mul_f32_e32 v104, v24, v6
	v_mul_f32_e32 v7, v5, v7
	v_mul_f32_e32 v105, v25, v7
	v_mul_f32_e32 v8, v5, v8
	v_mul_f32_e32 v106, v26, v8
	v_mul_f32_e32 v9, v5, v9
	v_mul_f32_e32 v107, v27, v9
	global_store_dwordx4 v3, v[104:107], s[6:7] offset:2048
	v_lshlrev_b32_e32 v6, 16, v78
	v_and_b32_e32 v7, 0xffff0000, v78
	v_lshlrev_b32_e32 v8, 16, v79
	v_and_b32_e32 v9, 0xffff0000, v79
	v_mul_f32_e32 v6, v5, v6
	v_mul_f32_e32 v108, v28, v6
	v_mul_f32_e32 v7, v5, v7
	v_mul_f32_e32 v109, v29, v7
	v_mul_f32_e32 v8, v5, v8
	v_mul_f32_e32 v110, v30, v8
	v_mul_f32_e32 v9, v5, v9
	v_mul_f32_e32 v111, v31, v9
	global_store_dwordx4 v3, v[108:111], s[6:7] offset:3072
